# attention: L row-sum via 16x16x32 MFMA with persistent indicator operand, V frag reads in MFMA order with counted waits, QK fast path with S0-first MFMA order overlapping exp
# speedup vs baseline: 1.0267x; 1.0267x over previous
; __device__ __forceinline__ void attn_item(LAS unsigned char* lds, const bf16_t* Q, const bf16_t* Kb, const bf16_t* VT, bf16_t* aout, const float* subg, float lam, float omli, float kbound, int head, int qb) {
;     int tid_ = threadIdx.x; asm volatile("" : "+v"(tid_));
;     const int tid = tid_, lane = tid & 63, r = lane & 31, hh = lane >> 5; const int wid = __builtin_amdgcn_readfirstlane(tid >> 6);
;     const int comp = wid >> 2, qt = wid & 3; const int q0 = qb * 128 + qt * 32, q = q0 + r; const int nt = 2 * qb + 2;
;     bf16x8 qf[4];
;     { const bf16_t* Qp = Q + ((size_t)(head * 2 + comp) * S + q) * 64 + 8 * hh;
; #pragma unroll
;       for (int s = 0; s < 4; ++s) qf[s] = *(const bf16x8*)(Qp + 16 * s); }
;     const int srow = tid >> 3, sch = tid & 7;
;     const char* bK1 = (const char*)(Kb + (size_t)(head * 2 + 0) * S * 64); const char* bK2 = (const char*)(Kb + (size_t)(head * 2 + 1) * S * 64);
;     const char* bV0 = (const char*)(VT + (size_t)head * 256 * 128 * 64); const char* bV1 = bV0 + 8192;
;     const unsigned koff = srow * 128 + sch * 16, voff = koff;
;     const unsigned dK1 = srow * AT_ROWB + sch * 16, dK2 = AT_K2 + dK1, dV0 = AT_VOFF + dK1, dV1 = AT_VOFF + 64 * AT_ROWB + dK1;
;     u32x4 ks0 = *(const u32x4*)(bK1 + koff), ks1 = *(const u32x4*)(bK2 + koff), vs0 = *(const u32x4*)(bV0 + voff), vs1 = *(const u32x4*)(bV1 + voff);
;     *(LAS u32x4*)(lds + dK1) = ks0; *(LAS u32x4*)(lds + dK2) = ks1; *(LAS u32x4*)(lds + dV0) = vs0; *(LAS u32x4*)(lds + dV1) = vs1;
;     ks0 = *(const u32x4*)(bK1 + 8192 + koff); ks1 = *(const u32x4*)(bK2 + 8192 + koff);
;     asm volatile("" : "+v"(qf[0]), "+v"(qf[1]), "+v"(qf[2]), "+v"(qf[3]));
;     __syncthreads();
;     f32x16 O[4];
; #pragma unroll
;     for (int e = 0; e < 4; ++e)
; #pragma unroll
;         for (int i = 0; i < 16; ++i) O[e][i] = 0.f;
;     float qn2 = 0.f;
; #pragma unroll
;     for (int s = 0; s < 4; ++s)
; #pragma unroll
;         for (int e = 0; e < 8; ++e) { const float v = bf2f((bf16_t)qf[s][e]); qn2 += v * v; }
;     const float sbound = __builtin_sqrtf(half_swap_sum(qn2)) * kbound;
;     const bool online = __builtin_amdgcn_ballot_w64(!(sbound <= 100.f)) != 0ull;
;     float mrun = 0.f;
;     f32x16 L;
; #pragma unroll
;     for (int i = 0; i < 16; ++i) L[i] = 0.f;
;     bf16x8 pf[4];
; #pragma unroll
;     for (int i = 0; i < 4; ++i) pf[i] = (bf16x8){0, 0, 0, 0, 0, 0, 0, 0};
.LBB0_292:
	v_cndmask_b32_e64 v0, 0, 1, s[6:7]
	s_ashr_i32 s20, s17, 2
	v_readfirstlane_b32 s0, v0
	s_lshl_b32 s19, s0, 1
	s_and_b32 s0, s20, -2
	s_and_b32 s1, s17, 1
	v_mov_b32_e32 v2, v182
	s_or_b32 s21, s0, s1
	s_bfe_u32 s18, s17, 0x20001
	v_readfirstlane_b32 s26, v2
	s_sub_i32 s0, 0x7f, s21
	s_bfe_u32 s23, s26, 0x20006
	s_ashr_i32 s24, s26, 8
	s_lshl_b32 s1, s0, 7
	s_lshl_b32 s4, s23, 5
	s_lshl_b32 s22, s18, 1
	s_or_b32 s33, s4, s1
	s_add_i32 s4, s24, s22
	s_ashr_i32 s5, s4, 31
	s_lshl_b32 s0, s0, 1
	s_lshl_b64 s[4:5], s[4:5], 21
	s_add_u32 s4, s11, s4
	v_and_b32_e32 v227, 31, v2
	s_addc_u32 s5, s12, s5
	s_lshl_b32 s1, s18, 22
	v_or_b32_e32 v202, s33, v227
	s_add_u32 s8, s13, s1
	v_ashrrev_i32_e32 v203, 31, v202
	s_addc_u32 s9, s14, 0
	v_bfe_u32 v226, v2, 5, 1
	v_lshlrev_b64 v[0:1], 7, v[202:203]
	s_add_u32 s38, s8, 0x200000
	v_lshl_add_u64 v[0:1], s[4:5], 0, v[0:1]
	v_lshlrev_b32_e32 v112, 4, v226
	s_addc_u32 s39, s9, 0
	v_lshl_add_u64 v[16:17], v[0:1], 0, v[112:113]
	s_add_u32 s42, s15, s1
	v_lshlrev_b32_e32 v0, 4, v2
	v_ashrrev_i32_e32 v19, 3, v2
	s_addc_u32 s43, s16, 0
	v_and_b32_e32 v18, 0x70, v0
	s_add_u32 s46, s42, 0x2000
	v_lshl_or_b32 v20, v19, 7, v18
	s_addc_u32 s47, s43, 0
	global_load_dwordx4 v[0:3], v20, s[8:9]
	global_load_dwordx4 v[4:7], v20, s[38:39]
	global_load_dwordx4 v[8:11], v20, s[42:43]
	global_load_dwordx4 v[12:15], v20, s[46:47]
	global_load_dwordx4 v[114:117], v[16:17], off offset:96
	global_load_dwordx4 v[118:121], v[16:17], off offset:64
	global_load_dwordx4 v[122:125], v[16:17], off offset:32
	global_load_dwordx4 v[126:129], v[16:17], off
	s_add_u32 s50, s8, 0x2000
	s_addc_u32 s51, s9, 0
	s_add_u32 s62, s8, 0x202000
	s_addc_u32 s63, s9, 0
	global_load_dwordx4 v[130:133], v20, s[50:51]
	global_load_dwordx4 v[134:137], v20, s[62:63]
	v_mad_u64_u32 v[212:213], s[4:5], v19, s66, v[18:19]
	v_add_u32_e32 v213, 0, v212
	v_mov_b32_e32 v21, v113
	v_lshl_add_u64 v[204:205], s[8:9], 0, v[20:21]
	v_lshl_add_u64 v[206:207], s[38:39], 0, v[20:21]
	v_lshl_add_u64 v[208:209], s[42:43], 0, v[20:21]
	v_lshl_add_u64 v[210:211], s[46:47], 0, v[20:21]
	s_mul_i32 s1, s24, 0x2400
	v_mad_u32_u24 v228, v227, s66, v112
	v_add_u32_e32 v229, s1, v228
	s_waitcnt vmcnt(9)
	ds_write_b128 v213, v[0:3]
	s_waitcnt vmcnt(8)
	ds_write_b128 v213, v[4:7] offset:9216
	s_waitcnt vmcnt(7)
	ds_write_b128 v213, v[8:11] offset:36864
	s_waitcnt vmcnt(6)
	ds_write_b128 v213, v[12:15] offset:46080
	s_waitcnt vmcnt(2)
	s_nop 0
	v_and_b32_e32 v2, 0xffff0000, v126
	v_lshlrev_b32_e32 v0, 16, v126
	v_mul_f32_e32 v2, v2, v2
	v_lshlrev_b32_e32 v3, 16, v127
	v_fmac_f32_e32 v2, v0, v0
	v_and_b32_e32 v4, 0xffff0000, v127
	v_fmac_f32_e32 v2, v3, v3
	v_lshlrev_b32_e32 v5, 16, v128
	v_fmac_f32_e32 v2, v4, v4
	v_and_b32_e32 v6, 0xffff0000, v128
	v_fmac_f32_e32 v2, v5, v5
	v_lshlrev_b32_e32 v7, 16, v129
	v_fmac_f32_e32 v2, v6, v6
	v_and_b32_e32 v8, 0xffff0000, v129
	v_fmac_f32_e32 v2, v7, v7
	v_lshlrev_b32_e32 v9, 16, v122
	v_fmac_f32_e32 v2, v8, v8
	v_and_b32_e32 v10, 0xffff0000, v122
	v_fmac_f32_e32 v2, v9, v9
	v_lshlrev_b32_e32 v11, 16, v123
	v_fmac_f32_e32 v2, v10, v10
	v_and_b32_e32 v12, 0xffff0000, v123
	v_fmac_f32_e32 v2, v11, v11
	v_lshlrev_b32_e32 v13, 16, v124
	v_fmac_f32_e32 v2, v12, v12
	v_and_b32_e32 v14, 0xffff0000, v124
	v_fmac_f32_e32 v2, v13, v13
	v_lshlrev_b32_e32 v15, 16, v125
	v_fmac_f32_e32 v2, v14, v14
	v_and_b32_e32 v16, 0xffff0000, v125
	v_fmac_f32_e32 v2, v15, v15
	v_lshlrev_b32_e32 v17, 16, v118
	v_fmac_f32_e32 v2, v16, v16
	v_and_b32_e32 v18, 0xffff0000, v118
	v_fmac_f32_e32 v2, v17, v17
	v_lshlrev_b32_e32 v19, 16, v119
	v_fmac_f32_e32 v2, v18, v18
	v_and_b32_e32 v20, 0xffff0000, v119
	v_fmac_f32_e32 v2, v19, v19
	v_lshlrev_b32_e32 v21, 16, v120
	v_fmac_f32_e32 v2, v20, v20
	v_and_b32_e32 v22, 0xffff0000, v120
	v_fmac_f32_e32 v2, v21, v21
	v_lshlrev_b32_e32 v23, 16, v121
	v_fmac_f32_e32 v2, v22, v22
	v_and_b32_e32 v24, 0xffff0000, v121
	v_fmac_f32_e32 v2, v23, v23
	v_lshlrev_b32_e32 v25, 16, v114
	v_fmac_f32_e32 v2, v24, v24
	v_and_b32_e32 v26, 0xffff0000, v114
	v_and_b32_e32 v1, 0xffff0000, v115
	v_fmac_f32_e32 v2, v25, v25
	v_lshlrev_b32_e32 v0, 16, v115
	v_fmac_f32_e32 v2, v26, v26
	v_pk_mul_f32 v[0:1], v[0:1], v[0:1]
	s_waitcnt lgkmcnt(0)
	v_add_f32_e32 v0, v0, v2
	v_add_f32_e32 v2, v1, v0
	v_and_b32_e32 v1, 0xffff0000, v116
	v_lshlrev_b32_e32 v0, 16, v116
	v_pk_mul_f32 v[0:1], v[0:1], v[0:1]
	s_barrier
	v_add_f32_e32 v0, v0, v2
	v_add_f32_e32 v2, v1, v0
	v_and_b32_e32 v1, 0xffff0000, v117
	v_lshlrev_b32_e32 v0, 16, v117
	v_pk_mul_f32 v[0:1], v[0:1], v[0:1]
	s_nop 0
	v_add_f32_e32 v0, v0, v2
	v_add_f32_e32 v0, v1, v0
	v_mov_b32_e32 v1, v0
	s_nop 1
	v_permlane32_swap_b32_e32 v0, v1
	v_add_f32_e32 v0, v0, v1
	v_mul_f32_e32 v1, 0x4f800000, v0
	v_cmp_gt_f32_e32 vcc, s67, v0
	s_nop 1
	v_cndmask_b32_e32 v0, v0, v1, vcc
	v_sqrt_f32_e32 v1, v0
	s_nop 0
	v_add_u32_e32 v2, -1, v1
	v_fma_f32 v3, -v2, v1, v0
	v_cmp_ge_f32_e64 s[4:5], 0, v3
	v_add_u32_e32 v3, 1, v1
	s_nop 0
	v_cndmask_b32_e64 v2, v1, v2, s[4:5]
	v_fma_f32 v1, -v3, v1, v0
	v_cmp_lt_f32_e64 s[4:5], 0, v1
	s_nop 1
	v_cndmask_b32_e64 v1, v2, v3, s[4:5]
	v_mul_f32_e32 v2, 0x37800000, v1
	v_cndmask_b32_e32 v1, v1, v2, vcc
	v_cmp_class_f32_e32 vcc, v0, v219
	s_nop 1
	v_cndmask_b32_e32 v0, v1, v0, vcc
	v_mul_f32_e32 v0, v225, v0
	v_cmp_nge_f32_e32 vcc, s68, v0
	s_cmp_lg_u64 vcc, 0
	s_cselect_b64 s[64:65], -1, 0
	s_or_b32 s40, s33, 31
	s_or_b32 s41, s0, 1
	s_cmpk_lt_u32 s26, 0x100
	s_cselect_b64 s[4:5], -1, 0
	s_mov_b64 s[0:1], -1
	s_and_b64 vcc, exec, s[4:5]
	s_cbranch_vccnz .LBB0_310
	s_cmpk_gt_i32 s21, 0x7f
	s_cbranch_scc1 .LBB0_306
; #define LAS __attribute__((address_space(3)))
; __device__ __forceinline__ float bf2f(bf16_t v) { return __uint_as_float(((unsigned)v) << 16); }
; #define MFMA32(a, b, c) __builtin_amdgcn_mfma_f32_32x32x16_bf16((a), (b), (c), 0, 0, 0)
; __device__ __forceinline__ void at_pv_half(const LAS unsigned char* vp, const bf16x8 (&pf)[4], f32x16 (&O)[4], f32x16& L) {
;     bf16x8 va[8], vb[8];
; #pragma unroll
;     for (int e = 0; e < 2; ++e)
; #pragma unroll
;         for (int ks = 0; ks < 4; ++ks) va[e * 4 + ks] = *(const LAS bf16x8*)(vp + e * 32 * AT_ROWB + 32 * ks);
; #pragma unroll
;     for (int e = 0; e < 2; ++e)
; #pragma unroll
;         for (int ks = 0; ks < 4; ++ks) vb[e * 4 + ks] = *(const LAS bf16x8*)(vp + (2 + e) * 32 * AT_ROWB + 32 * ks);
;     const short one = (short)0x3F80; const bf16x8 ones = {one, one, one, one, one, one, one, one};
;     __builtin_amdgcn_sched_barrier(0);
;     __builtin_amdgcn_s_setprio(1);
; #pragma unroll
;     for (int ks = 0; ks < 4; ++ks) L = MFMA32(ones, pf[ks], L);
;     __builtin_amdgcn_sched_barrier(0);
; #pragma unroll
;     for (int ks = 0; ks < 4; ++ks) { O[0] = MFMA32(va[ks], pf[ks], O[0]); O[1] = MFMA32(va[4 + ks], pf[ks], O[1]); }
; #pragma unroll
;     for (int ks = 0; ks < 4; ++ks) { O[2] = MFMA32(vb[ks], pf[ks], O[2]); O[3] = MFMA32(vb[4 + ks], pf[ks], O[3]); }
;     __builtin_amdgcn_s_setprio(0);
; }
; __device__ __forceinline__ void attn_item(LAS unsigned char* lds, const bf16_t* Q, const bf16_t* Kb, const bf16_t* VT, bf16_t* aout, const float* subg, float lam, float omli, float kbound, int head, int qb) {
;     ...
;     f32x16 O[4];
; #pragma unroll
;     for (int e = 0; e < 4; ++e)
; #pragma unroll
;         for (int i = 0; i < 16; ++i) O[e][i] = 0.f;
;     float qn2 = 0.f;
; #pragma unroll
;     for (int s = 0; s < 4; ++s)
; #pragma unroll
;         for (int e = 0; e < 8; ++e) { const float v = bf2f((bf16_t)qf[s][e]); qn2 += v * v; }
;     const float sbound = __builtin_sqrtf(half_swap_sum(qn2)) * kbound;
;     const bool online = __builtin_amdgcn_ballot_w64(!(sbound <= 100.f)) != 0ull;
;     float mrun = 0.f;
;     f32x16 L;
; #pragma unroll
;     for (int i = 0; i < 16; ++i) L[i] = 0.f;
;     bf16x8 pf[4];
; #pragma unroll
;     for (int i = 0; i < 4; ++i) pf[i] = (bf16x8){0, 0, 0, 0, 0, 0, 0, 0};
	s_lshl_b32 s0, s20, 1
	s_and_b32 s0, s0, -4
	s_or_b32 s0, s19, s0
	v_mov_b32_e32 v14, v113
	v_mov_b32_e32 v15, v113
	s_sub_i32 s0, 0x100, s0
	v_mov_b32_e32 v0, v113
	v_mov_b32_e32 v1, v113
	v_mov_b32_e32 v2, v113
	v_mov_b32_e32 v3, v113
	v_mov_b32_e32 v4, v113
	v_mov_b32_e32 v5, v113
	v_mov_b32_e32 v6, v113
	v_mov_b32_e32 v7, v113
	v_mov_b32_e32 v8, v113
	v_mov_b32_e32 v9, v113
	v_mov_b32_e32 v10, v113
	v_mov_b32_e32 v11, v113
	v_mov_b32_e32 v12, v113
	v_mov_b32_e32 v13, v113
	v_mov_b64_e32 v[30:31], v[14:15]
	v_mov_b64_e32 v[46:47], v[14:15]
	v_mov_b64_e32 v[62:63], v[14:15]
	v_mov_b64_e32 v[78:79], v[14:15]
	s_waitcnt vmcnt(0)
	v_mov_b64_e32 v[140:141], v[136:137]
	v_mov_b64_e32 v[144:145], v[132:133]
	v_add_u32_e32 v230, 0, v229
	v_lshlrev_b32_e32 v231, 2, v226
	s_max_i32 s0, s0, 1
	s_mov_b32 s45, 0
	v_mov_b32_e32 v214, 0
	s_mov_b32 s1, 63
	v_mov_b32_e32 v92, 0
	v_mov_b32_e32 v93, 0
	v_mov_b32_e32 v94, 0
	v_mov_b32_e32 v95, 0
	v_mov_b32_e32 v84, 0
	v_mov_b32_e32 v85, 0
	v_mov_b32_e32 v86, 0
	v_mov_b32_e32 v87, 0
	v_mov_b32_e32 v88, 0
	v_mov_b32_e32 v89, 0
	v_mov_b32_e32 v90, 0
	v_mov_b32_e32 v91, 0
	v_mov_b32_e32 v80, 0
	v_mov_b32_e32 v81, 0
	v_mov_b32_e32 v82, 0
	v_mov_b32_e32 v83, 0
	v_mov_b64_e32 v[28:29], v[12:13]
	v_mov_b64_e32 v[26:27], v[10:11]
	v_mov_b64_e32 v[24:25], v[8:9]
	v_mov_b64_e32 v[22:23], v[6:7]
	v_mov_b64_e32 v[20:21], v[4:5]
	v_mov_b64_e32 v[18:19], v[2:3]
	v_mov_b64_e32 v[16:17], v[0:1]
	v_mov_b64_e32 v[44:45], v[12:13]
	v_mov_b64_e32 v[42:43], v[10:11]
	v_mov_b64_e32 v[40:41], v[8:9]
	v_mov_b64_e32 v[38:39], v[6:7]
	v_mov_b64_e32 v[36:37], v[4:5]
	v_mov_b64_e32 v[34:35], v[2:3]
	v_mov_b64_e32 v[32:33], v[0:1]
	v_mov_b64_e32 v[60:61], v[12:13]
	v_mov_b64_e32 v[58:59], v[10:11]
	v_mov_b64_e32 v[56:57], v[8:9]
	v_mov_b64_e32 v[54:55], v[6:7]
	v_mov_b64_e32 v[52:53], v[4:5]
	v_mov_b64_e32 v[50:51], v[2:3]
	v_mov_b64_e32 v[48:49], v[0:1]
	v_mov_b64_e32 v[76:77], v[12:13]
	v_mov_b64_e32 v[74:75], v[10:11]
	v_mov_b64_e32 v[72:73], v[8:9]
	v_mov_b64_e32 v[70:71], v[6:7]
	v_mov_b64_e32 v[68:69], v[4:5]
	v_mov_b64_e32 v[66:67], v[2:3]
	v_mov_b64_e32 v[64:65], v[0:1]
	v_mov_b64_e32 v[138:139], v[134:135]
	v_mov_b64_e32 v[142:143], v[130:131]
	s_mov_b32 vcc_lo, 0xf0f00f0f
	s_mov_b32 vcc_hi, 0xf0f00f0f
	v_mov_b32_e32 v77, s52
	s_nop 1
	v_cndmask_b32_e32 v76, 0, v77, vcc
	v_mov_b32_e32 v77, v76
	v_mov_b32_e32 v78, v76
	v_mov_b32_e32 v79, v76
.LBB0_295:
	s_add_i32 s44, s45, 1
	s_bitcmp1_b32 s44, 0
	s_cselect_b32 s53, 0x4800, 0
	s_min_i32 s58, s44, s41
	s_lshl_b64 s[54:55], s[58:59], 14
	v_lshl_add_u64 v[96:97], v[208:209], 0, s[54:55]
	v_lshl_add_u64 v[98:99], v[210:211], 0, s[54:55]
	global_load_dwordx4 v[146:149], v[96:97], off
	global_load_dwordx4 v[150:153], v[98:99], off
	s_add_i32 s56, s53, 0
	s_cmp_eq_u32 s45, 0
	s_cselect_b64 s[54:55], -1, 0
	s_add_i32 s53, s1, 0xffffff81
	s_cmp_gt_i32 s53, s40
	s_cselect_b64 s[60:61], -1, 0
	s_or_b64 s[54:55], s[54:55], s[60:61]
	s_and_b64 vcc, exec, s[54:55]
	s_cbranch_vccnz .LBB0_297
	v_add_u32_e32 v184, s56, v228
	ds_read_b128 v[96:99], v184 offset:36864
	ds_read_b128 v[154:157], v184 offset:41472
	ds_read_b128 v[170:173], v184 offset:46080
	ds_read_b128 v[236:239], v184 offset:50688
	ds_read_b128 v[100:103], v184 offset:36896
	ds_read_b128 v[158:161], v184 offset:41504
	ds_read_b128 v[174:177], v184 offset:46112
	ds_read_b128 v[240:243], v184 offset:50720
	ds_read_b128 v[104:107], v184 offset:36928
	ds_read_b128 v[162:165], v184 offset:41536
	ds_read_b128 v[178:181], v184 offset:46144
	ds_read_b128 v[244:247], v184 offset:50752
	ds_read_b128 v[108:111], v184 offset:36960
	ds_read_b128 v[166:169], v184 offset:41568
	ds_read_b128 v[232:235], v184 offset:46176
	ds_read_b128 v[248:251], v184 offset:50784
	s_setprio 1
	v_mfma_f32_16x16x32_bf16 v[64:67], v[76:79], v[80:83], v[64:67]
	v_mfma_f32_16x16x32_bf16 v[64:67], v[76:79], v[88:91], v[64:67]
	v_mfma_f32_16x16x32_bf16 v[64:67], v[76:79], v[84:87], v[64:67]
	v_mfma_f32_16x16x32_bf16 v[64:67], v[76:79], v[92:95], v[64:67]
	s_waitcnt lgkmcnt(15)
	v_mfma_f32_32x32x16_bf16 v[48:63], v[96:99], v[80:83], v[48:63]
	s_waitcnt lgkmcnt(14)
	v_mfma_f32_32x32x16_bf16 v[32:47], v[154:157], v[80:83], v[32:47]
	s_waitcnt lgkmcnt(13)
	v_mfma_f32_32x32x16_bf16 v[16:31], v[170:173], v[80:83], v[16:31]
	s_waitcnt lgkmcnt(12)
	v_mfma_f32_32x32x16_bf16 v[0:15], v[236:239], v[80:83], v[0:15]
	s_waitcnt lgkmcnt(11)
	v_mfma_f32_32x32x16_bf16 v[48:63], v[100:103], v[88:91], v[48:63]
	s_waitcnt lgkmcnt(10)
	v_mfma_f32_32x32x16_bf16 v[32:47], v[158:161], v[88:91], v[32:47]
	s_waitcnt lgkmcnt(9)
	v_mfma_f32_32x32x16_bf16 v[16:31], v[174:177], v[88:91], v[16:31]
	s_waitcnt lgkmcnt(8)
	v_mfma_f32_32x32x16_bf16 v[0:15], v[240:243], v[88:91], v[0:15]
	s_waitcnt lgkmcnt(7)
	v_mfma_f32_32x32x16_bf16 v[48:63], v[104:107], v[84:87], v[48:63]
	s_waitcnt lgkmcnt(6)
	v_mfma_f32_32x32x16_bf16 v[32:47], v[162:165], v[84:87], v[32:47]
	s_waitcnt lgkmcnt(5)
	v_mfma_f32_32x32x16_bf16 v[16:31], v[178:181], v[84:87], v[16:31]
	s_waitcnt lgkmcnt(4)
	v_mfma_f32_32x32x16_bf16 v[0:15], v[244:247], v[84:87], v[0:15]
	s_waitcnt lgkmcnt(3)
	v_mfma_f32_32x32x16_bf16 v[48:63], v[108:111], v[92:95], v[48:63]
	s_waitcnt lgkmcnt(2)
	v_mfma_f32_32x32x16_bf16 v[32:47], v[166:169], v[92:95], v[32:47]
	s_waitcnt lgkmcnt(1)
	v_mfma_f32_32x32x16_bf16 v[16:31], v[232:235], v[92:95], v[16:31]
	s_waitcnt lgkmcnt(0)
	v_mfma_f32_32x32x16_bf16 v[0:15], v[248:251], v[92:95], v[0:15]
	s_setprio 0
; #define LAS __attribute__((address_space(3)))
; #define MFMA32(a, b, c) __builtin_amdgcn_mfma_f32_32x32x16_bf16((a), (b), (c), 0, 0, 0)
; #define AT_WRITE_K(jn) do { LAS unsigned char* n_ = lds + ((jn) & 1) * AT_KST; *(LAS u32x4*)(n_ + dK1) = ks0; *(LAS u32x4*)(n_ + dK2) = ks1; } while (0)
; __device__ __forceinline__ void at_qk_half(const bool ONLINE, const bool act, const LAS unsigned char* kp, u32x4& pfa, u32x4& pfb, const char* pga, const char* pgb, const bf16x8 (&qf)[4], int q, int q0, int kbase, int hh, float& mrun, f32x16 (&O)[4], f32x16& L, bf16x8 (&pf)[4]) {
;     __builtin_amdgcn_s_setprio(3);
;     bf16x8 kf[8];
; #pragma unroll
;     for (int s = 0; s < 4; ++s) { kf[2 * s] = *(const LAS bf16x8*)(kp + 32 * s); kf[2 * s + 1] = *(const LAS bf16x8*)(kp + 32 * AT_ROWB + 32 * s); }
;     __builtin_amdgcn_sched_barrier(0);
;     pfa = *(const u32x4*)pga; pfb = *(const u32x4*)pgb;
;     __builtin_amdgcn_sched_barrier(0);
;     if (!act) { __builtin_amdgcn_s_setprio(0); return; }
;     f32x16 s0, s1;
; #pragma unroll
;     for (int i = 0; i < 16; ++i) { s0[i] = 0.f; s1[i] = 0.f; }
; #pragma unroll
;     for (int s = 0; s < 4; ++s) { s0 = MFMA32(kf[2 * s], qf[s], s0); s1 = MFMA32(kf[2 * s + 1], qf[s], s1); }
;     __builtin_amdgcn_s_setprio(0);
;     if (kbase + 63 > q0) {
;         const int kb = kbase + 4 * hh;
; #pragma unroll
;         for (int i = 0; i < 16; ++i) { const int kv = kb + (i & 3) + 8 * (i >> 2); if (kv > q) s0[i] = -INFINITY; if (kv + 32 > q) s1[i] = -INFINITY; }
; __device__ __forceinline__ void attn_item(LAS unsigned char* lds, const bf16_t* Q, const bf16_t* Kb, const bf16_t* VT, bf16_t* aout, const float* subg, float lam, float omli, float kbound, int head, int qb) {
;     ...
;             const LAS unsigned char* stg = lds + (j & 1) * AT_KST; const LAS unsigned char* pst = lds + ((j + 1) & 1) * AT_KST; const int kbase = j * 64;
;             AT_ISSUE_V(j + 1);
;             if (j > 0 && kbase - 64 <= qmax) at_pv_half(pst + vfo, pf, O, L);
;             AT_WRITE_K(j + 1);
;             __syncthreads();
;             __builtin_amdgcn_s_setprio(3);
;             { const int jc_ = (j + 2) < ntm1 ? (j + 2) : ntm1; const size_t ko_ = (size_t)jc_ * 8192; const char* pga = bK1 + ko_ + koff; const char* pgb = bK2 + ko_ + koff;
;               at_qk_half(online, kbase <= qmax, stg + kfo, ks0, ks1, pga, pgb, qf, q, q0, kbase, hh, mrun, O, L, pf); }
.LBB0_297:
	s_bitcmp1_b32 s45, 0
	v_add_u32_e32 v232, s56, v212
	s_cselect_b32 s53, 0x4800, 0
	s_sub_i32 s57, s1, 63
	s_waitcnt vmcnt(3)
	ds_write_b128 v232, v[142:145]
	s_waitcnt vmcnt(2)
	ds_write_b128 v232, v[138:141] offset:9216
	s_waitcnt lgkmcnt(0)
	s_barrier
	s_setprio 3
	s_add_i32 s45, s45, 2
	s_min_i32 s58, s45, s41
	s_lshl_b64 s[54:55], s[58:59], 13
	v_lshl_add_u64 v[100:101], v[204:205], 0, s[54:55]
	v_lshl_add_u64 v[102:103], v[206:207], 0, s[54:55]
	s_cmp_gt_i32 s57, s40
	v_add_u32_e32 v104, s53, v230
	s_setprio 3
	ds_read_b128 v[96:99], v104
	ds_read_b128 v[166:169], v104 offset:32
	ds_read_b128 v[162:165], v104 offset:64
	ds_read_b128 v[154:157], v104 offset:96
	ds_read_b128 v[178:181], v104 offset:4608
	ds_read_b128 v[170:173], v104 offset:4640
	ds_read_b128 v[174:177], v104 offset:4672
	ds_read_b128 v[158:161], v104 offset:4704
	global_load_dwordx4 v[142:145], v[100:101], off
	global_load_dwordx4 v[138:141], v[102:103], off
	s_cbranch_scc1 .LBB0_304
	s_cmp_le_i32 s1, s33
	s_cbranch_scc0 .Lmy_slow1
	s_andn2_b64 vcc, exec, s[64:65]
	s_cbranch_vccz .Lmy_slow1
	s_waitcnt lgkmcnt(7)
	v_mfma_f32_32x32x16_bf16 v[96:111], v[96:99], v[126:129], 0
	s_waitcnt lgkmcnt(6)
	v_mfma_f32_32x32x16_bf16 v[96:111], v[166:169], v[122:125], v[96:111]
	s_waitcnt lgkmcnt(5)
	v_mfma_f32_32x32x16_bf16 v[96:111], v[162:165], v[118:121], v[96:111]
	s_waitcnt lgkmcnt(4)
	v_mfma_f32_32x32x16_bf16 v[96:111], v[154:157], v[114:117], v[96:111]
	s_waitcnt lgkmcnt(3)
	v_mfma_f32_32x32x16_bf16 v[80:95], v[178:181], v[126:129], 0
	s_waitcnt lgkmcnt(2)
	v_mfma_f32_32x32x16_bf16 v[80:95], v[170:173], v[122:125], v[80:95]
	s_nop 3
	v_exp_f32_e32 v96, v96
	v_exp_f32_e32 v97, v97
	v_exp_f32_e32 v98, v98
	v_exp_f32_e32 v99, v99
	s_waitcnt lgkmcnt(1)
	v_mfma_f32_32x32x16_bf16 v[80:95], v[174:177], v[118:121], v[80:95]
	v_exp_f32_e32 v100, v100
	v_exp_f32_e32 v101, v101
	v_exp_f32_e32 v102, v102
	v_exp_f32_e32 v103, v103
	s_waitcnt lgkmcnt(0)
	v_mfma_f32_32x32x16_bf16 v[80:95], v[158:161], v[114:117], v[80:95]
	s_setprio 0
	v_exp_f32_e32 v104, v104
	v_exp_f32_e32 v105, v105
	v_exp_f32_e32 v106, v106
	v_exp_f32_e32 v107, v107
	v_exp_f32_e32 v108, v108
	v_exp_f32_e32 v109, v109
	v_exp_f32_e32 v110, v110
	v_exp_f32_e32 v111, v111
	s_nop 3
	v_exp_f32_e32 v154, v80
	v_exp_f32_e32 v155, v81
	v_exp_f32_e32 v156, v82
	v_exp_f32_e32 v157, v83
	v_exp_f32_e32 v158, v84
	v_exp_f32_e32 v159, v85
	v_exp_f32_e32 v160, v86
	v_exp_f32_e32 v161, v87
	v_exp_f32_e32 v162, v88
	v_exp_f32_e32 v163, v89
	v_exp_f32_e32 v164, v90
	v_exp_f32_e32 v165, v91
	v_exp_f32_e32 v166, v92
	v_exp_f32_e32 v167, v93
	v_exp_f32_e32 v168, v94
	v_exp_f32_e32 v169, v95
	v_cvt_pk_bf16_f32 v80, v96, v97
	v_cvt_pk_bf16_f32 v81, v98, v99
	v_cvt_pk_bf16_f32 v82, v100, v101
	v_cvt_pk_bf16_f32 v83, v102, v103
	v_cvt_pk_bf16_f32 v84, v154, v155
	v_cvt_pk_bf16_f32 v85, v156, v157
	v_cvt_pk_bf16_f32 v86, v158, v159
	v_cvt_pk_bf16_f32 v87, v160, v161
	v_cvt_pk_bf16_f32 v88, v104, v105
	v_cvt_pk_bf16_f32 v89, v106, v107
	v_cvt_pk_bf16_f32 v90, v108, v109
	v_cvt_pk_bf16_f32 v91, v110, v111
	v_cvt_pk_bf16_f32 v92, v162, v163
	v_cvt_pk_bf16_f32 v93, v164, v165
	v_cvt_pk_bf16_f32 v94, v166, v167
	v_cvt_pk_bf16_f32 v95, v168, v169
	s_branch .LBB0_304
.Lmy_slow1:
	s_waitcnt lgkmcnt(7)
	v_mfma_f32_32x32x16_bf16 v[96:111], v[96:99], v[126:129], 0
	s_waitcnt lgkmcnt(3)
	v_mfma_f32_32x32x16_bf16 v[80:95], v[178:181], v[126:129], 0
	v_mfma_f32_32x32x16_bf16 v[96:111], v[166:169], v[122:125], v[96:111]
	s_waitcnt lgkmcnt(2)
	v_mfma_f32_32x32x16_bf16 v[80:95], v[170:173], v[122:125], v[80:95]
	v_mfma_f32_32x32x16_bf16 v[96:111], v[162:165], v[118:121], v[96:111]
	s_waitcnt lgkmcnt(1)
	v_mfma_f32_32x32x16_bf16 v[80:95], v[174:177], v[118:121], v[80:95]
	v_mfma_f32_32x32x16_bf16 v[96:111], v[154:157], v[114:117], v[96:111]
	s_waitcnt lgkmcnt(0)
	v_mfma_f32_32x32x16_bf16 v[80:95], v[158:161], v[114:117], v[80:95]
	s_setprio 0
	s_cmp_le_i32 s1, s33
	s_cbranch_scc1 .LBB0_300
	v_add_u32_e32 v154, s1, v231
	v_subrev_u32_e32 v156, 31, v154
	v_subrev_u32_e32 v155, 63, v154
	v_cmp_le_i32_e32 vcc, v156, v202
	s_nop 4
	v_cndmask_b32_e32 v80, v221, v80, vcc
	v_cmp_lt_i32_e32 vcc, v155, v202
	s_nop 1
	v_cndmask_b32_e32 v97, v221, v97, vcc
	v_cmp_le_i32_e32 vcc, v155, v202
	v_subrev_u32_e32 v155, 30, v154
	s_nop 0
	v_cndmask_b32_e32 v96, v221, v96, vcc
	v_cmp_le_i32_e32 vcc, v155, v202
	v_subrev_u32_e32 v155, 61, v154
	s_nop 0
	v_cndmask_b32_e32 v81, v221, v81, vcc
	v_cmp_le_i32_e32 vcc, v155, v202
	v_subrev_u32_e32 v155, 29, v154
	s_nop 0
	v_cndmask_b32_e32 v98, v221, v98, vcc
	v_cmp_le_i32_e32 vcc, v155, v202
	v_subrev_u32_e32 v155, 60, v154
	s_nop 0
	v_cndmask_b32_e32 v82, v221, v82, vcc
	v_cmp_le_i32_e32 vcc, v155, v202
	v_subrev_u32_e32 v155, 28, v154
	s_nop 0
	v_cndmask_b32_e32 v99, v221, v99, vcc
	v_cmp_le_i32_e32 vcc, v155, v202
	v_subrev_u32_e32 v155, 55, v154
	s_nop 0
	v_cndmask_b32_e32 v83, v221, v83, vcc
	v_cmp_le_i32_e32 vcc, v155, v202
	v_subrev_u32_e32 v155, 23, v154
	s_nop 0
	v_cndmask_b32_e32 v100, v221, v100, vcc
	v_cmp_le_i32_e32 vcc, v155, v202
	v_subrev_u32_e32 v155, 54, v154
	s_nop 0
	v_cndmask_b32_e32 v84, v221, v84, vcc
	v_cmp_le_i32_e32 vcc, v155, v202
	v_subrev_u32_e32 v155, 22, v154
	s_nop 0
	v_cndmask_b32_e32 v101, v221, v101, vcc
	v_cmp_le_i32_e32 vcc, v155, v202
	v_subrev_u32_e32 v155, 53, v154
	s_nop 0
	v_cndmask_b32_e32 v85, v221, v85, vcc
	v_cmp_le_i32_e32 vcc, v155, v202
	v_subrev_u32_e32 v155, 21, v154
	s_nop 0
	v_cndmask_b32_e32 v102, v221, v102, vcc
	v_cmp_le_i32_e32 vcc, v155, v202
	v_subrev_u32_e32 v155, 52, v154
	s_nop 0
	v_cndmask_b32_e32 v86, v221, v86, vcc
	v_cmp_le_i32_e32 vcc, v155, v202
; __device__ __forceinline__ void at_qk_half(const bool ONLINE, const bool act, const LAS unsigned char* kp, u32x4& pfa, u32x4& pfb, const char* pga, const char* pgb, const bf16x8 (&qf)[4], int q, int q0, int kbase, int hh, float& mrun, f32x16 (&O)[4], f32x16& L, bf16x8 (&pf)[4]) {
;     ...
;     if (kbase + 63 > q0) {
;         const int kb = kbase + 4 * hh;
; #pragma unroll
;         for (int i = 0; i < 16; ++i) { const int kv = kb + (i & 3) + 8 * (i >> 2); if (kv > q) s0[i] = -INFINITY; if (kv + 32 > q) s1[i] = -INFINITY; }
;     }
	v_subrev_u32_e32 v155, 20, v154
	s_nop 0
	v_cndmask_b32_e32 v103, v221, v103, vcc
	v_cmp_le_i32_e32 vcc, v155, v202
	v_subrev_u32_e32 v155, 47, v154
	s_nop 0
	v_cndmask_b32_e32 v87, v221, v87, vcc
	v_cmp_le_i32_e32 vcc, v155, v202
	v_add_u32_e32 v155, -15, v154
	s_nop 0
	v_cndmask_b32_e32 v104, v221, v104, vcc
	v_cmp_le_i32_e32 vcc, v155, v202
	v_subrev_u32_e32 v155, 46, v154
	s_nop 0
	v_cndmask_b32_e32 v88, v221, v88, vcc
	v_cmp_le_i32_e32 vcc, v155, v202
	v_add_u32_e32 v155, -14, v154
	s_nop 0
	v_cndmask_b32_e32 v105, v221, v105, vcc
	v_cmp_le_i32_e32 vcc, v155, v202
	v_subrev_u32_e32 v155, 45, v154
	s_nop 0
	v_cndmask_b32_e32 v89, v221, v89, vcc
	v_cmp_le_i32_e32 vcc, v155, v202
	v_add_u32_e32 v155, -13, v154
	s_nop 0
	v_cndmask_b32_e32 v106, v221, v106, vcc
	v_cmp_le_i32_e32 vcc, v155, v202
	v_subrev_u32_e32 v155, 44, v154
	s_nop 0
	v_cndmask_b32_e32 v90, v221, v90, vcc
	v_cmp_le_i32_e32 vcc, v155, v202
	v_add_u32_e32 v155, -12, v154
	s_nop 0
	v_cndmask_b32_e32 v107, v221, v107, vcc
	v_cmp_le_i32_e32 vcc, v155, v202
	v_subrev_u32_e32 v155, 39, v154
	s_nop 0
	v_cndmask_b32_e32 v91, v221, v91, vcc
	v_cmp_le_i32_e32 vcc, v155, v202
	v_add_u32_e32 v155, -7, v154
	s_nop 0
	v_cndmask_b32_e32 v108, v221, v108, vcc
	v_cmp_le_i32_e32 vcc, v155, v202
	v_subrev_u32_e32 v155, 38, v154
	s_nop 0
	v_cndmask_b32_e32 v92, v221, v92, vcc
	v_cmp_le_i32_e32 vcc, v155, v202
	v_add_u32_e32 v155, -6, v154
	s_nop 0
	v_cndmask_b32_e32 v109, v221, v109, vcc
	v_cmp_le_i32_e32 vcc, v155, v202
	v_subrev_u32_e32 v155, 37, v154
	s_nop 0
	v_cndmask_b32_e32 v93, v221, v93, vcc
	v_cmp_le_i32_e32 vcc, v155, v202
	v_add_u32_e32 v155, -5, v154
	s_nop 0
	v_cndmask_b32_e32 v110, v221, v110, vcc
	v_cmp_le_i32_e32 vcc, v155, v202
	v_subrev_u32_e32 v155, 36, v154
	v_add_u32_e32 v154, -4, v154
	v_cndmask_b32_e32 v94, v221, v94, vcc
	v_cmp_le_i32_e32 vcc, v155, v202
	s_nop 1
	v_cndmask_b32_e32 v111, v221, v111, vcc
	v_cmp_le_i32_e32 vcc, v154, v202
	s_nop 1
	v_cndmask_b32_e32 v95, v221, v95, vcc
; __device__ __forceinline__ float half_swap_max(float v) { auto rr = __builtin_amdgcn_permlane32_swap(__float_as_uint(v), __float_as_uint(v), false, false); return fmaxf(__uint_as_float(rr[0]), __uint_as_float(rr[1])); }
; __device__ __forceinline__ float at_max3(float a, float b, float c) { float r; asm("v_max3_f32 %0, %1, %2, %3" : "=v"(r) : "v"(a), "v"(b), "v"(c)); return r; }
; __device__ __forceinline__ void at_qk_half(const bool ONLINE, const bool act, const LAS unsigned char* kp, u32x4& pfa, u32x4& pfb, const char* pga, const char* pgb, const bf16x8 (&qf)[4], int q, int q0, int kbase, int hh, float& mrun, f32x16 (&O)[4], f32x16& L, bf16x8 (&pf)[4]) {
;     ...
;     if (ONLINE) {
; #pragma unroll
;         for (int i = 0; i < 16; ++i) { s0[i] -= mrun; s1[i] -= mrun; }
;         float mx = fmaxf(s0[0], s1[0]);
; #pragma unroll
;         for (int i = 1; i < 16; ++i) mx = at_max3(mx, s0[i], s1[i]);
;         mx = half_swap_max(mx);
;         if (__builtin_amdgcn_ballot_w64(mx > 8.f) != 0ull) {
;             const float d = fmaxf(mx, 0.f); const float alpha = __builtin_amdgcn_exp2f(-d); mrun += d;
; #pragma unroll
;             for (int e = 0; e < 4; ++e)
; #pragma unroll
;                 for (int i = 0; i < 16; ++i) O[e][i] *= alpha;
; #pragma unroll
;             for (int i = 0; i < 16; ++i) { L[i] *= alpha; s0[i] -= d; s1[i] -= d; }
;         }
;     }
.LBB0_300:
	s_andn2_b64 vcc, exec, s[64:65]
	s_cbranch_vccnz .LBB0_303
	s_nop 4
	v_pk_add_f32 v[96:97], v[96:97], v[214:215] op_sel_hi:[1,0] neg_lo:[0,1] neg_hi:[0,1]
	s_nop 0
	v_pk_add_f32 v[80:81], v[80:81], v[214:215] op_sel_hi:[1,0] neg_lo:[0,1] neg_hi:[0,1]
	v_pk_add_f32 v[98:99], v[98:99], v[214:215] op_sel_hi:[1,0] neg_lo:[0,1] neg_hi:[0,1]
	v_max_f32_e32 v154, v96, v80
	v_max3_f32 v154, v154, v97, v81
	v_pk_add_f32 v[82:83], v[82:83], v[214:215] op_sel_hi:[1,0] neg_lo:[0,1] neg_hi:[0,1]
	v_pk_add_f32 v[100:101], v[100:101], v[214:215] op_sel_hi:[1,0] neg_lo:[0,1] neg_hi:[0,1]
	v_max3_f32 v154, v154, v98, v82
	v_pk_add_f32 v[84:85], v[84:85], v[214:215] op_sel_hi:[1,0] neg_lo:[0,1] neg_hi:[0,1]
	v_max3_f32 v154, v154, v99, v83
	v_pk_add_f32 v[102:103], v[102:103], v[214:215] op_sel_hi:[1,0] neg_lo:[0,1] neg_hi:[0,1]
	v_max3_f32 v154, v154, v100, v84
	v_pk_add_f32 v[86:87], v[86:87], v[214:215] op_sel_hi:[1,0] neg_lo:[0,1] neg_hi:[0,1]
	v_max3_f32 v154, v154, v101, v85
	v_pk_add_f32 v[104:105], v[104:105], v[214:215] op_sel_hi:[1,0] neg_lo:[0,1] neg_hi:[0,1]
	v_max3_f32 v154, v154, v102, v86
	v_pk_add_f32 v[88:89], v[88:89], v[214:215] op_sel_hi:[1,0] neg_lo:[0,1] neg_hi:[0,1]
	v_max3_f32 v154, v154, v103, v87
	v_pk_add_f32 v[106:107], v[106:107], v[214:215] op_sel_hi:[1,0] neg_lo:[0,1] neg_hi:[0,1]
	v_max3_f32 v154, v154, v104, v88
	v_pk_add_f32 v[90:91], v[90:91], v[214:215] op_sel_hi:[1,0] neg_lo:[0,1] neg_hi:[0,1]
	v_max3_f32 v154, v154, v105, v89
	v_pk_add_f32 v[108:109], v[108:109], v[214:215] op_sel_hi:[1,0] neg_lo:[0,1] neg_hi:[0,1]
	v_max3_f32 v154, v154, v106, v90
	v_pk_add_f32 v[92:93], v[92:93], v[214:215] op_sel_hi:[1,0] neg_lo:[0,1] neg_hi:[0,1]
	v_max3_f32 v154, v154, v107, v91
	v_pk_add_f32 v[110:111], v[110:111], v[214:215] op_sel_hi:[1,0] neg_lo:[0,1] neg_hi:[0,1]
	v_max3_f32 v154, v154, v108, v92
	v_pk_add_f32 v[94:95], v[94:95], v[214:215] op_sel_hi:[1,0] neg_lo:[0,1] neg_hi:[0,1]
	v_max3_f32 v154, v154, v109, v93
	s_nop 0
	v_max3_f32 v154, v154, v110, v94
	s_nop 0
	v_max3_f32 v154, v154, v111, v95
	s_nop 0
	v_mov_b32_e32 v155, v154
	s_nop 1
	v_permlane32_swap_b32_e32 v154, v155
	v_max_f32_e32 v155, v155, v155
	v_max_f32_e32 v154, v154, v154
	v_max_f32_e32 v154, v154, v155
	v_cmp_lt_f32_e32 vcc, s25, v154
	s_cbranch_vccz .LBB0_303
	v_max_f32_e32 v154, v154, v154
	v_max_f32_e32 v155, 0, v154
	v_exp_f32_e64 v154, -v155
	v_add_f32_e32 v214, v214, v155
	v_sub_f32_e32 v111, v111, v155
	v_sub_f32_e32 v110, v110, v155
	v_pk_mul_f32 v[62:63], v[62:63], v[154:155] op_sel_hi:[1,0]
	v_pk_mul_f32 v[60:61], v[60:61], v[154:155] op_sel_hi:[1,0]
	v_pk_mul_f32 v[58:59], v[58:59], v[154:155] op_sel_hi:[1,0]
	v_pk_mul_f32 v[56:57], v[56:57], v[154:155] op_sel_hi:[1,0]
	v_pk_mul_f32 v[54:55], v[54:55], v[154:155] op_sel_hi:[1,0]
	v_pk_mul_f32 v[52:53], v[52:53], v[154:155] op_sel_hi:[1,0]
	v_pk_mul_f32 v[50:51], v[50:51], v[154:155] op_sel_hi:[1,0]
	v_pk_mul_f32 v[48:49], v[48:49], v[154:155] op_sel_hi:[1,0]
	v_pk_mul_f32 v[46:47], v[46:47], v[154:155] op_sel_hi:[1,0]
	v_pk_mul_f32 v[44:45], v[44:45], v[154:155] op_sel_hi:[1,0]
	v_pk_mul_f32 v[42:43], v[42:43], v[154:155] op_sel_hi:[1,0]
	v_pk_mul_f32 v[40:41], v[40:41], v[154:155] op_sel_hi:[1,0]
	v_pk_mul_f32 v[38:39], v[38:39], v[154:155] op_sel_hi:[1,0]
	v_pk_mul_f32 v[36:37], v[36:37], v[154:155] op_sel_hi:[1,0]
	v_pk_mul_f32 v[34:35], v[34:35], v[154:155] op_sel_hi:[1,0]
	v_pk_mul_f32 v[32:33], v[32:33], v[154:155] op_sel_hi:[1,0]
	v_pk_mul_f32 v[30:31], v[30:31], v[154:155] op_sel_hi:[1,0]
	v_pk_mul_f32 v[28:29], v[28:29], v[154:155] op_sel_hi:[1,0]
	v_pk_mul_f32 v[26:27], v[26:27], v[154:155] op_sel_hi:[1,0]
	v_pk_mul_f32 v[24:25], v[24:25], v[154:155] op_sel_hi:[1,0]
	v_pk_mul_f32 v[22:23], v[22:23], v[154:155] op_sel_hi:[1,0]
	v_pk_mul_f32 v[20:21], v[20:21], v[154:155] op_sel_hi:[1,0]
	v_pk_mul_f32 v[18:19], v[18:19], v[154:155] op_sel_hi:[1,0]
	v_pk_mul_f32 v[16:17], v[16:17], v[154:155] op_sel_hi:[1,0]
	v_pk_mul_f32 v[14:15], v[14:15], v[154:155] op_sel_hi:[1,0]
	v_pk_mul_f32 v[12:13], v[12:13], v[154:155] op_sel_hi:[1,0]
	v_pk_mul_f32 v[10:11], v[10:11], v[154:155] op_sel_hi:[1,0]
	v_pk_mul_f32 v[8:9], v[8:9], v[154:155] op_sel_hi:[1,0]
	v_pk_mul_f32 v[6:7], v[6:7], v[154:155] op_sel_hi:[1,0]
	v_pk_mul_f32 v[4:5], v[4:5], v[154:155] op_sel_hi:[1,0]
	v_pk_mul_f32 v[2:3], v[2:3], v[154:155] op_sel_hi:[1,0]
	v_pk_mul_f32 v[0:1], v[0:1], v[154:155] op_sel_hi:[1,0]
	v_pk_mul_f32 v[74:75], v[74:75], v[154:155] op_sel_hi:[1,0]
	v_pk_mul_f32 v[72:73], v[72:73], v[154:155] op_sel_hi:[1,0]
	v_pk_mul_f32 v[70:71], v[70:71], v[154:155] op_sel_hi:[1,0]
	v_pk_mul_f32 v[68:69], v[68:69], v[154:155] op_sel_hi:[1,0]
	v_pk_mul_f32 v[66:67], v[66:67], v[154:155] op_sel_hi:[1,0]
	v_pk_mul_f32 v[64:65], v[64:65], v[154:155] op_sel_hi:[1,0]
	v_sub_f32_e32 v109, v109, v155
	v_sub_f32_e32 v108, v108, v155
	v_sub_f32_e32 v107, v107, v155
	v_sub_f32_e32 v106, v106, v155
	v_sub_f32_e32 v105, v105, v155
	v_sub_f32_e32 v104, v104, v155
	v_sub_f32_e32 v103, v103, v155
	v_sub_f32_e32 v102, v102, v155
	v_sub_f32_e32 v101, v101, v155
	v_sub_f32_e32 v100, v100, v155
	v_sub_f32_e32 v99, v99, v155
	v_sub_f32_e32 v98, v98, v155
	v_sub_f32_e32 v97, v97, v155
	v_sub_f32_e32 v96, v96, v155
	v_sub_f32_e32 v95, v95, v155
	v_sub_f32_e32 v94, v94, v155
	v_sub_f32_e32 v93, v93, v155
	v_sub_f32_e32 v92, v92, v155
	v_sub_f32_e32 v91, v91, v155
	v_sub_f32_e32 v90, v90, v155
	v_sub_f32_e32 v89, v89, v155
	v_sub_f32_e32 v88, v88, v155
	v_sub_f32_e32 v87, v87, v155
	v_sub_f32_e32 v86, v86, v155
	v_sub_f32_e32 v85, v85, v155
	v_sub_f32_e32 v84, v84, v155
	v_sub_f32_e32 v83, v83, v155
	v_sub_f32_e32 v82, v82, v155
	v_sub_f32_e32 v81, v81, v155
	v_sub_f32_e32 v80, v80, v155

; #define LAS __attribute__((address_space(3)))
; #define MFMA32(a, b, c) __builtin_amdgcn_mfma_f32_32x32x16_bf16((a), (b), (c), 0, 0, 0)
; __device__ __forceinline__ void at_pv_half(const LAS unsigned char* vp, const bf16x8 (&pf)[4], f32x16 (&O)[4], f32x16& L) {
;     bf16x8 va[8], vb[8];
; #pragma unroll
;     for (int e = 0; e < 2; ++e)
; #pragma unroll
;         for (int ks = 0; ks < 4; ++ks) va[e * 4 + ks] = *(const LAS bf16x8*)(vp + e * 32 * AT_ROWB + 32 * ks);
; #pragma unroll
;     for (int e = 0; e < 2; ++e)
; #pragma unroll
;         for (int ks = 0; ks < 4; ++ks) vb[e * 4 + ks] = *(const LAS bf16x8*)(vp + (2 + e) * 32 * AT_ROWB + 32 * ks);
;     const short one = (short)0x3F80; const bf16x8 ones = {one, one, one, one, one, one, one, one};
;     __builtin_amdgcn_sched_barrier(0);
;     __builtin_amdgcn_s_setprio(1);
; #pragma unroll
;     for (int ks = 0; ks < 4; ++ks) L = MFMA32(ones, pf[ks], L);
;     __builtin_amdgcn_sched_barrier(0);
; #pragma unroll
;     for (int ks = 0; ks < 4; ++ks) { O[0] = MFMA32(va[ks], pf[ks], O[0]); O[1] = MFMA32(va[4 + ks], pf[ks], O[1]); }
; #pragma unroll
;     for (int ks = 0; ks < 4; ++ks) { O[2] = MFMA32(vb[ks], pf[ks], O[2]); O[3] = MFMA32(vb[4 + ks], pf[ks], O[3]); }
;     __builtin_amdgcn_s_setprio(0);
; }
.LBB0_307:
	s_mov_b32 vcc_lo, 0xf0f00f0f
	s_mov_b32 vcc_hi, 0xf0f00f0f
	v_mov_b32_e32 v77, s52
	s_nop 1
	v_cndmask_b32_e32 v76, 0, v77, vcc
	v_mov_b32_e32 v77, v76
	v_mov_b32_e32 v78, v76
	v_mov_b32_e32 v79, v76
	s_lshl_b32 s0, s41, 6
	s_cmp_le_i32 s0, s40
	s_cbranch_scc0 .LBB0_309
	v_add_u32_e32 v166, 0, v228
	v_add_u32_e32 v184, 0xd800, v166
	ds_read_b128 v[96:99], v166 offset:55296
	ds_read_b128 v[100:103], v166 offset:55328
	ds_read_b128 v[104:107], v166 offset:55360
	ds_read_b128 v[108:111], v166 offset:55392
	s_waitcnt vmcnt(0)
	ds_read_b128 v[138:141], v166 offset:59904
	ds_read_b128 v[142:145], v166 offset:59936
	ds_read_b128 v[146:149], v166 offset:59968
	ds_read_b128 v[150:153], v166 offset:60000
	ds_read_b128 v[154:157], v166 offset:64512
	ds_read_b128 v[158:161], v166 offset:64544
	ds_read_b128 v[162:165], v166 offset:64576
	ds_read_b128 v[166:169], v166 offset:64608
	ds_read_b128 v[170:173], v184 offset:13824
	ds_read_b128 v[174:177], v184 offset:13856
	ds_read_b128 v[178:181], v184 offset:13888
	ds_read_b128 v[184:187], v184 offset:13920
	s_setprio 1
	v_mfma_f32_16x16x32_bf16 v[64:67], v[76:79], v[80:83], v[64:67]
	v_mfma_f32_16x16x32_bf16 v[64:67], v[76:79], v[88:91], v[64:67]
	v_mfma_f32_16x16x32_bf16 v[64:67], v[76:79], v[84:87], v[64:67]
	v_mfma_f32_16x16x32_bf16 v[64:67], v[76:79], v[92:95], v[64:67]
	s_waitcnt lgkmcnt(14)
	v_mfma_f32_32x32x16_bf16 v[48:63], v[96:99], v[80:83], v[48:63]
	s_waitcnt lgkmcnt(11)
	v_mfma_f32_32x32x16_bf16 v[32:47], v[138:141], v[80:83], v[32:47]
	s_waitcnt lgkmcnt(7)
	v_mfma_f32_32x32x16_bf16 v[16:31], v[154:157], v[80:83], v[16:31]
	s_waitcnt lgkmcnt(3)
	v_mfma_f32_32x32x16_bf16 v[0:15], v[170:173], v[80:83], v[0:15]
	v_mfma_f32_32x32x16_bf16 v[48:63], v[100:103], v[88:91], v[48:63]
	v_mfma_f32_32x32x16_bf16 v[32:47], v[142:145], v[88:91], v[32:47]
	v_mfma_f32_32x32x16_bf16 v[16:31], v[158:161], v[88:91], v[16:31]
	s_waitcnt lgkmcnt(2)
	v_mfma_f32_32x32x16_bf16 v[0:15], v[174:177], v[88:91], v[0:15]
	v_mfma_f32_32x32x16_bf16 v[48:63], v[104:107], v[84:87], v[48:63]
	v_mfma_f32_32x32x16_bf16 v[32:47], v[146:149], v[84:87], v[32:47]
	v_mfma_f32_32x32x16_bf16 v[16:31], v[162:165], v[84:87], v[16:31]
	s_waitcnt lgkmcnt(1)
	v_mfma_f32_32x32x16_bf16 v[0:15], v[178:181], v[84:87], v[0:15]
	v_mfma_f32_32x32x16_bf16 v[48:63], v[108:111], v[92:95], v[48:63]
	v_mfma_f32_32x32x16_bf16 v[32:47], v[150:153], v[92:95], v[32:47]
	v_mfma_f32_32x32x16_bf16 v[16:31], v[166:169], v[92:95], v[16:31]
	s_waitcnt lgkmcnt(0)
	v_mfma_f32_32x32x16_bf16 v[0:15], v[184:187], v[92:95], v[0:15]
	s_setprio 0

; #define LAS __attribute__((address_space(3)))
; __device__ __forceinline__ float bf2f(bf16_t v) { return __uint_as_float(((unsigned)v) << 16); }
; __device__ __forceinline__ float half_swap_sum(float v) { auto rr = __builtin_amdgcn_permlane32_swap(__float_as_uint(v), __float_as_uint(v), false, false); return __uint_as_float(rr[0]) + __uint_as_float(rr[1]); }
; #define MFMA32(a, b, c) __builtin_amdgcn_mfma_f32_32x32x16_bf16((a), (b), (c), 0, 0, 0)
; __device__ __forceinline__ void at_qk_half(const bool ONLINE, const bool act, const LAS unsigned char* kp, u32x4& pfa, u32x4& pfb, const char* pga, const char* pgb, const bf16x8 (&qf)[4], int q, int q0, int kbase, int hh, float& mrun, f32x16 (&O)[4], f32x16& L, bf16x8 (&pf)[4]) {
;     __builtin_amdgcn_s_setprio(3);
;     bf16x8 kf[8];
; #pragma unroll
;     for (int s = 0; s < 4; ++s) { kf[2 * s] = *(const LAS bf16x8*)(kp + 32 * s); kf[2 * s + 1] = *(const LAS bf16x8*)(kp + 32 * AT_ROWB + 32 * s); }
;     __builtin_amdgcn_sched_barrier(0);
;     pfa = *(const u32x4*)pga; pfb = *(const u32x4*)pgb;
;     __builtin_amdgcn_sched_barrier(0);
;     if (!act) { __builtin_amdgcn_s_setprio(0); return; }
;     f32x16 s0, s1;
; #pragma unroll
;     for (int i = 0; i < 16; ++i) { s0[i] = 0.f; s1[i] = 0.f; }
; #pragma unroll
;     for (int s = 0; s < 4; ++s) { s0 = MFMA32(kf[2 * s], qf[s], s0); s1 = MFMA32(kf[2 * s + 1], qf[s], s1); }
; __device__ __forceinline__ void attn_item(LAS unsigned char* lds, const bf16_t* Q, const bf16_t* Kb, const bf16_t* VT, bf16_t* aout, const float* subg, float lam, float omli, float kbound, int head, int qb) {
;     ...
;     f32x16 O[4];
; #pragma unroll
;     for (int e = 0; e < 4; ++e)
; #pragma unroll
;         for (int i = 0; i < 16; ++i) O[e][i] = 0.f;
;     float qn2 = 0.f;
; #pragma unroll
;     for (int s = 0; s < 4; ++s)
; #pragma unroll
;         for (int e = 0; e < 8; ++e) { const float v = bf2f((bf16_t)qf[s][e]); qn2 += v * v; }
;     const float sbound = __builtin_sqrtf(half_swap_sum(qn2)) * kbound;
;     const bool online = __builtin_amdgcn_ballot_w64(!(sbound <= 100.f)) != 0ull;
;     float mrun = 0.f;
;     f32x16 L;
; #pragma unroll
;     for (int i = 0; i < 16; ++i) L[i] = 0.f;
;     bf16x8 pf[4];
; #pragma unroll
;     for (int i = 0; i < 4; ++i) pf[i] = (bf16x8){0, 0, 0, 0, 0, 0, 0, 0};
.LBB0_310:
	s_and_b64 vcc, exec, s[0:1]
	s_cbranch_vccz .LBB0_326
	s_cmpk_gt_i32 s21, 0x7f
	s_cbranch_scc1 .LBB0_324
	s_lshl_b32 s0, s20, 1
	s_and_b32 s0, s0, -4
	s_or_b32 s0, s19, s0
	s_nop 1
	v_mov_b32_e32 v14, v113
	v_mov_b32_e32 v15, v113
	s_sub_i32 s0, 0x100, s0
	v_mov_b32_e32 v0, v113
	v_mov_b32_e32 v1, v113
	v_mov_b32_e32 v2, v113
	v_mov_b32_e32 v3, v113
	v_mov_b32_e32 v4, v113
	v_mov_b32_e32 v5, v113
	v_mov_b32_e32 v6, v113
	v_mov_b32_e32 v7, v113
	v_mov_b32_e32 v8, v113
	v_mov_b32_e32 v9, v113
	v_mov_b32_e32 v10, v113
	v_mov_b32_e32 v11, v113
	v_mov_b32_e32 v12, v113
	v_mov_b32_e32 v13, v113
	v_mov_b64_e32 v[30:31], v[14:15]
	v_mov_b64_e32 v[46:47], v[14:15]
	v_mov_b64_e32 v[62:63], v[14:15]
	v_mov_b64_e32 v[78:79], v[14:15]
	v_lshlrev_b32_e32 v175, 2, v226
	s_max_i32 s44, s0, 1
	s_mov_b32 s53, 0
	v_mov_b32_e32 v174, 0
	s_mov_b32 s45, 63
	v_mov_b32_e32 v92, 0
	v_mov_b32_e32 v93, 0
	v_mov_b32_e32 v94, 0
	v_mov_b32_e32 v95, 0
	v_mov_b32_e32 v84, 0
	v_mov_b32_e32 v85, 0
	v_mov_b32_e32 v86, 0
	v_mov_b32_e32 v87, 0
	v_mov_b32_e32 v88, 0
	v_mov_b32_e32 v89, 0
	v_mov_b32_e32 v90, 0
	v_mov_b32_e32 v91, 0
	v_mov_b32_e32 v80, 0
	v_mov_b32_e32 v81, 0
	v_mov_b32_e32 v82, 0
	v_mov_b32_e32 v83, 0
	v_mov_b64_e32 v[28:29], v[12:13]
	v_mov_b64_e32 v[26:27], v[10:11]
	v_mov_b64_e32 v[24:25], v[8:9]
	v_mov_b64_e32 v[22:23], v[6:7]
	v_mov_b64_e32 v[20:21], v[4:5]
	v_mov_b64_e32 v[18:19], v[2:3]
	v_mov_b64_e32 v[16:17], v[0:1]
	v_mov_b64_e32 v[44:45], v[12:13]
	v_mov_b64_e32 v[42:43], v[10:11]
	v_mov_b64_e32 v[40:41], v[8:9]
	v_mov_b64_e32 v[38:39], v[6:7]
	v_mov_b64_e32 v[36:37], v[4:5]
	v_mov_b64_e32 v[34:35], v[2:3]
	v_mov_b64_e32 v[32:33], v[0:1]
	v_mov_b64_e32 v[60:61], v[12:13]
	v_mov_b64_e32 v[58:59], v[10:11]
	v_mov_b64_e32 v[56:57], v[8:9]
	v_mov_b64_e32 v[54:55], v[6:7]
	v_mov_b64_e32 v[52:53], v[4:5]
	v_mov_b64_e32 v[50:51], v[2:3]
	v_mov_b64_e32 v[48:49], v[0:1]
	v_mov_b64_e32 v[76:77], v[12:13]
	v_mov_b64_e32 v[74:75], v[10:11]
	v_mov_b64_e32 v[72:73], v[8:9]
	v_mov_b64_e32 v[70:71], v[6:7]
	v_mov_b64_e32 v[68:69], v[4:5]
	v_mov_b64_e32 v[66:67], v[2:3]
	v_mov_b64_e32 v[64:65], v[0:1]
	s_mov_b32 vcc_lo, 0xf0f00f0f
	s_mov_b32 vcc_hi, 0xf0f00f0f
	v_mov_b32_e32 v77, s52
	s_nop 1
	v_cndmask_b32_e32 v76, 0, v77, vcc
	v_mov_b32_e32 v77, v76
	v_mov_b32_e32 v78, v76
	v_mov_b32_e32 v79, v76
.LBB0_313:
	s_bitcmp1_b32 s53, 0
	s_cselect_b32 s0, 0x4800, 0
	s_add_i32 s54, s0, 0
	s_sub_i32 s55, s45, 63
	s_cmp_le_i32 s55, s40
	s_cselect_b64 s[0:1], -1, 0
	s_add_i32 s56, s53, 1
	s_min_i32 s58, s56, s41
	s_lshl_b64 s[60:61], s[58:59], 14
	s_cmp_gt_i32 s55, s40
	s_setprio 3
	v_lshl_add_u64 v[100:101], v[208:209], 0, s[60:61]
	v_lshl_add_u64 v[102:103], v[210:211], 0, s[60:61]
	v_add_u32_e32 v104, s54, v229
	s_setprio 3
	ds_read_b128 v[96:99], v104
	ds_read_b128 v[158:161], v104 offset:32
	ds_read_b128 v[154:157], v104 offset:64
	ds_read_b128 v[146:149], v104 offset:96
	ds_read_b128 v[170:173], v104 offset:4608
	ds_read_b128 v[162:165], v104 offset:4640
	ds_read_b128 v[166:169], v104 offset:4672
	ds_read_b128 v[150:153], v104 offset:4704
	global_load_dwordx4 v[138:141], v[100:101], off
	global_load_dwordx4 v[142:145], v[102:103], off
	s_cbranch_scc1 .LBB0_320
	s_cmp_le_i32 s45, s33
	s_cbranch_scc0 .Lmy_slow2
	s_andn2_b64 vcc, exec, s[64:65]
	s_cbranch_vccz .Lmy_slow2
	s_waitcnt lgkmcnt(7)
	v_mfma_f32_32x32x16_bf16 v[96:111], v[96:99], v[126:129], 0
	s_waitcnt lgkmcnt(6)
	v_mfma_f32_32x32x16_bf16 v[96:111], v[158:161], v[122:125], v[96:111]
	s_waitcnt lgkmcnt(5)
	v_mfma_f32_32x32x16_bf16 v[96:111], v[154:157], v[118:121], v[96:111]
	s_waitcnt lgkmcnt(4)
	v_mfma_f32_32x32x16_bf16 v[96:111], v[146:149], v[114:117], v[96:111]
	s_waitcnt lgkmcnt(3)
	v_mfma_f32_32x32x16_bf16 v[80:95], v[170:173], v[126:129], 0
	s_waitcnt lgkmcnt(2)
	v_mfma_f32_32x32x16_bf16 v[80:95], v[162:165], v[122:125], v[80:95]
	s_nop 3
	v_exp_f32_e32 v96, v96
	v_exp_f32_e32 v97, v97
	v_exp_f32_e32 v98, v98
	v_exp_f32_e32 v99, v99
	s_waitcnt lgkmcnt(1)
	v_mfma_f32_32x32x16_bf16 v[80:95], v[166:169], v[118:121], v[80:95]
	v_exp_f32_e32 v100, v100
	v_exp_f32_e32 v101, v101
	v_exp_f32_e32 v102, v102
	v_exp_f32_e32 v103, v103
	s_waitcnt lgkmcnt(0)
	v_mfma_f32_32x32x16_bf16 v[80:95], v[150:153], v[114:117], v[80:95]
	s_setprio 0
	v_exp_f32_e32 v104, v104
	v_exp_f32_e32 v105, v105
	v_exp_f32_e32 v106, v106
	v_exp_f32_e32 v107, v107
	v_exp_f32_e32 v108, v108
	v_exp_f32_e32 v109, v109
	v_exp_f32_e32 v110, v110
	v_exp_f32_e32 v111, v111
	s_nop 3
	v_exp_f32_e32 v146, v80
	v_exp_f32_e32 v147, v81
	v_exp_f32_e32 v148, v82
	v_exp_f32_e32 v149, v83
	v_exp_f32_e32 v150, v84
	v_exp_f32_e32 v151, v85
	v_exp_f32_e32 v152, v86
	v_exp_f32_e32 v153, v87
	v_exp_f32_e32 v154, v88
	v_exp_f32_e32 v155, v89
	v_exp_f32_e32 v156, v90
	v_exp_f32_e32 v157, v91
	v_exp_f32_e32 v158, v92
	v_exp_f32_e32 v159, v93
	v_exp_f32_e32 v160, v94
	v_exp_f32_e32 v161, v95
	v_cvt_pk_bf16_f32 v80, v96, v97
	v_cvt_pk_bf16_f32 v81, v98, v99
	v_cvt_pk_bf16_f32 v82, v100, v101
	v_cvt_pk_bf16_f32 v83, v102, v103
	v_cvt_pk_bf16_f32 v84, v146, v147
	v_cvt_pk_bf16_f32 v85, v148, v149
	v_cvt_pk_bf16_f32 v86, v150, v151
	v_cvt_pk_bf16_f32 v87, v152, v153
	v_cvt_pk_bf16_f32 v88, v104, v105
	v_cvt_pk_bf16_f32 v89, v106, v107
	v_cvt_pk_bf16_f32 v90, v108, v109
	v_cvt_pk_bf16_f32 v91, v110, v111
	v_cvt_pk_bf16_f32 v92, v154, v155
	v_cvt_pk_bf16_f32 v93, v156, v157
	v_cvt_pk_bf16_f32 v94, v158, v159
	v_cvt_pk_bf16_f32 v95, v160, v161
	s_branch .LBB0_320
; #define LAS __attribute__((address_space(3)))
; #define MFMA32(a, b, c) __builtin_amdgcn_mfma_f32_32x32x16_bf16((a), (b), (c), 0, 0, 0)
; __device__ __forceinline__ void at_qk_half(const bool ONLINE, const bool act, const LAS unsigned char* kp, u32x4& pfa, u32x4& pfb, const char* pga, const char* pgb, const bf16x8 (&qf)[4], int q, int q0, int kbase, int hh, float& mrun, f32x16 (&O)[4], f32x16& L, bf16x8 (&pf)[4]) {
;     __builtin_amdgcn_s_setprio(3);
;     bf16x8 kf[8];
; #pragma unroll
;     for (int s = 0; s < 4; ++s) { kf[2 * s] = *(const LAS bf16x8*)(kp + 32 * s); kf[2 * s + 1] = *(const LAS bf16x8*)(kp + 32 * AT_ROWB + 32 * s); }
;     __builtin_amdgcn_sched_barrier(0);
;     pfa = *(const u32x4*)pga; pfb = *(const u32x4*)pgb;
;     __builtin_amdgcn_sched_barrier(0);
;     if (!act) { __builtin_amdgcn_s_setprio(0); return; }
;     f32x16 s0, s1;
; #pragma unroll
;     for (int i = 0; i < 16; ++i) { s0[i] = 0.f; s1[i] = 0.f; }
; #pragma unroll
;     for (int s = 0; s < 4; ++s) { s0 = MFMA32(kf[2 * s], qf[s], s0); s1 = MFMA32(kf[2 * s + 1], qf[s], s1); }
;     __builtin_amdgcn_s_setprio(0);
;     if (kbase + 63 > q0) {
;         const int kb = kbase + 4 * hh;
; #pragma unroll
;         for (int i = 0; i < 16; ++i) { const int kv = kb + (i & 3) + 8 * (i >> 2); if (kv > q) s0[i] = -INFINITY; if (kv + 32 > q) s1[i] = -INFINITY; }
;     }
.Lmy_slow2:
	s_waitcnt lgkmcnt(7)
	v_mfma_f32_32x32x16_bf16 v[96:111], v[96:99], v[126:129], 0
	s_waitcnt lgkmcnt(3)
	v_mfma_f32_32x32x16_bf16 v[80:95], v[170:173], v[126:129], 0
	v_mfma_f32_32x32x16_bf16 v[96:111], v[158:161], v[122:125], v[96:111]
	s_waitcnt lgkmcnt(2)
	v_mfma_f32_32x32x16_bf16 v[80:95], v[162:165], v[122:125], v[80:95]
	v_mfma_f32_32x32x16_bf16 v[96:111], v[154:157], v[118:121], v[96:111]
	s_waitcnt lgkmcnt(1)
	v_mfma_f32_32x32x16_bf16 v[80:95], v[166:169], v[118:121], v[80:95]
	v_mfma_f32_32x32x16_bf16 v[96:111], v[146:149], v[114:117], v[96:111]
	s_waitcnt lgkmcnt(0)
	v_mfma_f32_32x32x16_bf16 v[80:95], v[150:153], v[114:117], v[80:95]
	s_setprio 0
	s_cmp_le_i32 s45, s33
	s_cbranch_scc1 .LBB0_316
	v_add_u32_e32 v146, s45, v175
	v_subrev_u32_e32 v148, 31, v146
	v_subrev_u32_e32 v147, 63, v146
	v_cmp_le_i32_e32 vcc, v148, v202
	s_nop 4
	v_cndmask_b32_e32 v80, v221, v80, vcc
	v_cmp_lt_i32_e32 vcc, v147, v202
	s_nop 1
	v_cndmask_b32_e32 v97, v221, v97, vcc
	v_cmp_le_i32_e32 vcc, v147, v202
	v_subrev_u32_e32 v147, 30, v146
	s_nop 0
	v_cndmask_b32_e32 v96, v221, v96, vcc
	v_cmp_le_i32_e32 vcc, v147, v202
	v_subrev_u32_e32 v147, 61, v146
	s_nop 0
	v_cndmask_b32_e32 v81, v221, v81, vcc
	v_cmp_le_i32_e32 vcc, v147, v202
	v_subrev_u32_e32 v147, 29, v146
	s_nop 0
	v_cndmask_b32_e32 v98, v221, v98, vcc
	v_cmp_le_i32_e32 vcc, v147, v202
	v_subrev_u32_e32 v147, 60, v146
	s_nop 0
	v_cndmask_b32_e32 v82, v221, v82, vcc
	v_cmp_le_i32_e32 vcc, v147, v202
	v_subrev_u32_e32 v147, 28, v146
	s_nop 0
	v_cndmask_b32_e32 v99, v221, v99, vcc
	v_cmp_le_i32_e32 vcc, v147, v202
	v_subrev_u32_e32 v147, 55, v146
	s_nop 0
	v_cndmask_b32_e32 v83, v221, v83, vcc
	v_cmp_le_i32_e32 vcc, v147, v202
	v_subrev_u32_e32 v147, 23, v146
	s_nop 0
	v_cndmask_b32_e32 v100, v221, v100, vcc
	v_cmp_le_i32_e32 vcc, v147, v202
	v_subrev_u32_e32 v147, 54, v146
	s_nop 0
	v_cndmask_b32_e32 v84, v221, v84, vcc
	v_cmp_le_i32_e32 vcc, v147, v202
	v_subrev_u32_e32 v147, 22, v146
	s_nop 0
	v_cndmask_b32_e32 v101, v221, v101, vcc
	v_cmp_le_i32_e32 vcc, v147, v202
	v_subrev_u32_e32 v147, 53, v146
	s_nop 0
	v_cndmask_b32_e32 v85, v221, v85, vcc
	v_cmp_le_i32_e32 vcc, v147, v202
	v_subrev_u32_e32 v147, 21, v146
	s_nop 0
	v_cndmask_b32_e32 v102, v221, v102, vcc
	v_cmp_le_i32_e32 vcc, v147, v202
	v_subrev_u32_e32 v147, 52, v146
	s_nop 0
	v_cndmask_b32_e32 v86, v221, v86, vcc
	v_cmp_le_i32_e32 vcc, v147, v202
	v_subrev_u32_e32 v147, 20, v146
	s_nop 0
	v_cndmask_b32_e32 v103, v221, v103, vcc
	v_cmp_le_i32_e32 vcc, v147, v202
	v_subrev_u32_e32 v147, 47, v146
	s_nop 0
	v_cndmask_b32_e32 v87, v221, v87, vcc
	v_cmp_le_i32_e32 vcc, v147, v202
	v_add_u32_e32 v147, -15, v146
	s_nop 0
	v_cndmask_b32_e32 v104, v221, v104, vcc
	v_cmp_le_i32_e32 vcc, v147, v202
	v_subrev_u32_e32 v147, 46, v146
	s_nop 0
	v_cndmask_b32_e32 v88, v221, v88, vcc
	v_cmp_le_i32_e32 vcc, v147, v202
	v_add_u32_e32 v147, -14, v146
	s_nop 0
	v_cndmask_b32_e32 v105, v221, v105, vcc
	v_cmp_le_i32_e32 vcc, v147, v202
	v_subrev_u32_e32 v147, 45, v146
	s_nop 0
	v_cndmask_b32_e32 v89, v221, v89, vcc
	v_cmp_le_i32_e32 vcc, v147, v202
	v_add_u32_e32 v147, -13, v146
	s_nop 0
	v_cndmask_b32_e32 v106, v221, v106, vcc
	v_cmp_le_i32_e32 vcc, v147, v202
	v_subrev_u32_e32 v147, 44, v146
	s_nop 0
	v_cndmask_b32_e32 v90, v221, v90, vcc
	v_cmp_le_i32_e32 vcc, v147, v202
	v_add_u32_e32 v147, -12, v146
	s_nop 0
	v_cndmask_b32_e32 v107, v221, v107, vcc
	v_cmp_le_i32_e32 vcc, v147, v202
	v_subrev_u32_e32 v147, 39, v146
	s_nop 0
	v_cndmask_b32_e32 v91, v221, v91, vcc
	v_cmp_le_i32_e32 vcc, v147, v202
	v_add_u32_e32 v147, -7, v146
	s_nop 0
	v_cndmask_b32_e32 v108, v221, v108, vcc
	v_cmp_le_i32_e32 vcc, v147, v202
	v_subrev_u32_e32 v147, 38, v146
	s_nop 0
	v_cndmask_b32_e32 v92, v221, v92, vcc
	v_cmp_le_i32_e32 vcc, v147, v202
	v_add_u32_e32 v147, -6, v146
	s_nop 0
	v_cndmask_b32_e32 v109, v221, v109, vcc
	v_cmp_le_i32_e32 vcc, v147, v202
	v_subrev_u32_e32 v147, 37, v146
	s_nop 0
	v_cndmask_b32_e32 v93, v221, v93, vcc
	v_cmp_le_i32_e32 vcc, v147, v202
	v_add_u32_e32 v147, -5, v146
	s_nop 0
	v_cndmask_b32_e32 v110, v221, v110, vcc
	v_cmp_le_i32_e32 vcc, v147, v202
	v_subrev_u32_e32 v147, 36, v146
	v_add_u32_e32 v146, -4, v146
	v_cndmask_b32_e32 v94, v221, v94, vcc
	v_cmp_le_i32_e32 vcc, v147, v202
	s_nop 1
	v_cndmask_b32_e32 v111, v221, v111, vcc
	v_cmp_le_i32_e32 vcc, v146, v202
	s_nop 1
	v_cndmask_b32_e32 v95, v221, v95, vcc
; __device__ __forceinline__ float half_swap_max(float v) { auto rr = __builtin_amdgcn_permlane32_swap(__float_as_uint(v), __float_as_uint(v), false, false); return fmaxf(__uint_as_float(rr[0]), __uint_as_float(rr[1])); }
; __device__ __forceinline__ float at_max3(float a, float b, float c) { float r; asm("v_max3_f32 %0, %1, %2, %3" : "=v"(r) : "v"(a), "v"(b), "v"(c)); return r; }
; __device__ __forceinline__ void at_qk_half(const bool ONLINE, const bool act, const LAS unsigned char* kp, u32x4& pfa, u32x4& pfb, const char* pga, const char* pgb, const bf16x8 (&qf)[4], int q, int q0, int kbase, int hh, float& mrun, f32x16 (&O)[4], f32x16& L, bf16x8 (&pf)[4]) {
;     ...
;     if (ONLINE) {
; #pragma unroll
;         for (int i = 0; i < 16; ++i) { s0[i] -= mrun; s1[i] -= mrun; }
;         float mx = fmaxf(s0[0], s1[0]);
; #pragma unroll
;         for (int i = 1; i < 16; ++i) mx = at_max3(mx, s0[i], s1[i]);
;         mx = half_swap_max(mx);
;         if (__builtin_amdgcn_ballot_w64(mx > 8.f) != 0ull) {
;             const float d = fmaxf(mx, 0.f); const float alpha = __builtin_amdgcn_exp2f(-d); mrun += d;
; #pragma unroll
;             for (int e = 0; e < 4; ++e)
; #pragma unroll
;                 for (int i = 0; i < 16; ++i) O[e][i] *= alpha;
; #pragma unroll
;             for (int i = 0; i < 16; ++i) { L[i] *= alpha; s0[i] -= d; s1[i] -= d; }
;         }
;     }
.LBB0_316:
	s_andn2_b64 vcc, exec, s[64:65]
	s_cbranch_vccnz .LBB0_319
	s_nop 4
	v_pk_add_f32 v[96:97], v[96:97], v[174:175] op_sel_hi:[1,0] neg_lo:[0,1] neg_hi:[0,1]
	s_nop 0
	v_pk_add_f32 v[80:81], v[80:81], v[174:175] op_sel_hi:[1,0] neg_lo:[0,1] neg_hi:[0,1]
	v_pk_add_f32 v[98:99], v[98:99], v[174:175] op_sel_hi:[1,0] neg_lo:[0,1] neg_hi:[0,1]
	v_max_f32_e32 v146, v96, v80
	v_max3_f32 v146, v146, v97, v81
	v_pk_add_f32 v[82:83], v[82:83], v[174:175] op_sel_hi:[1,0] neg_lo:[0,1] neg_hi:[0,1]
	v_pk_add_f32 v[100:101], v[100:101], v[174:175] op_sel_hi:[1,0] neg_lo:[0,1] neg_hi:[0,1]
	v_max3_f32 v146, v146, v98, v82
	v_pk_add_f32 v[84:85], v[84:85], v[174:175] op_sel_hi:[1,0] neg_lo:[0,1] neg_hi:[0,1]
	v_max3_f32 v146, v146, v99, v83
	v_pk_add_f32 v[102:103], v[102:103], v[174:175] op_sel_hi:[1,0] neg_lo:[0,1] neg_hi:[0,1]
	v_max3_f32 v146, v146, v100, v84
	v_pk_add_f32 v[86:87], v[86:87], v[174:175] op_sel_hi:[1,0] neg_lo:[0,1] neg_hi:[0,1]
	v_max3_f32 v146, v146, v101, v85
	v_pk_add_f32 v[104:105], v[104:105], v[174:175] op_sel_hi:[1,0] neg_lo:[0,1] neg_hi:[0,1]
	v_max3_f32 v146, v146, v102, v86
	v_pk_add_f32 v[88:89], v[88:89], v[174:175] op_sel_hi:[1,0] neg_lo:[0,1] neg_hi:[0,1]
	v_max3_f32 v146, v146, v103, v87
	v_pk_add_f32 v[106:107], v[106:107], v[174:175] op_sel_hi:[1,0] neg_lo:[0,1] neg_hi:[0,1]
	v_max3_f32 v146, v146, v104, v88
	v_pk_add_f32 v[90:91], v[90:91], v[174:175] op_sel_hi:[1,0] neg_lo:[0,1] neg_hi:[0,1]
	v_max3_f32 v146, v146, v105, v89
	v_pk_add_f32 v[108:109], v[108:109], v[174:175] op_sel_hi:[1,0] neg_lo:[0,1] neg_hi:[0,1]
	v_max3_f32 v146, v146, v106, v90
	v_pk_add_f32 v[92:93], v[92:93], v[174:175] op_sel_hi:[1,0] neg_lo:[0,1] neg_hi:[0,1]
	v_max3_f32 v146, v146, v107, v91
	v_pk_add_f32 v[110:111], v[110:111], v[174:175] op_sel_hi:[1,0] neg_lo:[0,1] neg_hi:[0,1]
	v_max3_f32 v146, v146, v108, v92
	v_pk_add_f32 v[94:95], v[94:95], v[174:175] op_sel_hi:[1,0] neg_lo:[0,1] neg_hi:[0,1]
	v_max3_f32 v146, v146, v109, v93
	s_nop 0
	v_max3_f32 v146, v146, v110, v94
	s_nop 0
	v_max3_f32 v146, v146, v111, v95
	s_nop 0
	v_mov_b32_e32 v147, v146
	s_nop 1
	v_permlane32_swap_b32_e32 v146, v147
	v_max_f32_e32 v147, v147, v147
	v_max_f32_e32 v146, v146, v146
	v_max_f32_e32 v146, v146, v147
	v_cmp_lt_f32_e32 vcc, s25, v146
	s_cbranch_vccz .LBB0_319
	v_max_f32_e32 v146, v146, v146
	v_max_f32_e32 v147, 0, v146
	v_exp_f32_e64 v146, -v147
	v_add_f32_e32 v174, v174, v147
	v_sub_f32_e32 v111, v111, v147
	v_sub_f32_e32 v110, v110, v147
	v_pk_mul_f32 v[62:63], v[62:63], v[146:147] op_sel_hi:[1,0]
	v_pk_mul_f32 v[60:61], v[60:61], v[146:147] op_sel_hi:[1,0]
	v_pk_mul_f32 v[58:59], v[58:59], v[146:147] op_sel_hi:[1,0]
	v_pk_mul_f32 v[56:57], v[56:57], v[146:147] op_sel_hi:[1,0]
	v_pk_mul_f32 v[54:55], v[54:55], v[146:147] op_sel_hi:[1,0]
	v_pk_mul_f32 v[52:53], v[52:53], v[146:147] op_sel_hi:[1,0]
	v_pk_mul_f32 v[50:51], v[50:51], v[146:147] op_sel_hi:[1,0]
	v_pk_mul_f32 v[48:49], v[48:49], v[146:147] op_sel_hi:[1,0]
	v_pk_mul_f32 v[46:47], v[46:47], v[146:147] op_sel_hi:[1,0]
	v_pk_mul_f32 v[44:45], v[44:45], v[146:147] op_sel_hi:[1,0]
	v_pk_mul_f32 v[42:43], v[42:43], v[146:147] op_sel_hi:[1,0]
	v_pk_mul_f32 v[40:41], v[40:41], v[146:147] op_sel_hi:[1,0]
	v_pk_mul_f32 v[38:39], v[38:39], v[146:147] op_sel_hi:[1,0]
	v_pk_mul_f32 v[36:37], v[36:37], v[146:147] op_sel_hi:[1,0]
	v_pk_mul_f32 v[34:35], v[34:35], v[146:147] op_sel_hi:[1,0]
	v_pk_mul_f32 v[32:33], v[32:33], v[146:147] op_sel_hi:[1,0]
	v_pk_mul_f32 v[30:31], v[30:31], v[146:147] op_sel_hi:[1,0]
	v_pk_mul_f32 v[28:29], v[28:29], v[146:147] op_sel_hi:[1,0]
	v_pk_mul_f32 v[26:27], v[26:27], v[146:147] op_sel_hi:[1,0]
	v_pk_mul_f32 v[24:25], v[24:25], v[146:147] op_sel_hi:[1,0]
	v_pk_mul_f32 v[22:23], v[22:23], v[146:147] op_sel_hi:[1,0]
	v_pk_mul_f32 v[20:21], v[20:21], v[146:147] op_sel_hi:[1,0]
	v_pk_mul_f32 v[18:19], v[18:19], v[146:147] op_sel_hi:[1,0]
	v_pk_mul_f32 v[16:17], v[16:17], v[146:147] op_sel_hi:[1,0]
	v_pk_mul_f32 v[14:15], v[14:15], v[146:147] op_sel_hi:[1,0]
	v_pk_mul_f32 v[12:13], v[12:13], v[146:147] op_sel_hi:[1,0]
	v_pk_mul_f32 v[10:11], v[10:11], v[146:147] op_sel_hi:[1,0]
	v_pk_mul_f32 v[8:9], v[8:9], v[146:147] op_sel_hi:[1,0]
	v_pk_mul_f32 v[6:7], v[6:7], v[146:147] op_sel_hi:[1,0]
	v_pk_mul_f32 v[4:5], v[4:5], v[146:147] op_sel_hi:[1,0]
	v_pk_mul_f32 v[2:3], v[2:3], v[146:147] op_sel_hi:[1,0]
	v_pk_mul_f32 v[0:1], v[0:1], v[146:147] op_sel_hi:[1,0]
	v_pk_mul_f32 v[74:75], v[74:75], v[146:147] op_sel_hi:[1,0]
	v_pk_mul_f32 v[72:73], v[72:73], v[146:147] op_sel_hi:[1,0]
	v_pk_mul_f32 v[70:71], v[70:71], v[146:147] op_sel_hi:[1,0]
	v_pk_mul_f32 v[68:69], v[68:69], v[146:147] op_sel_hi:[1,0]
	v_pk_mul_f32 v[66:67], v[66:67], v[146:147] op_sel_hi:[1,0]
	v_pk_mul_f32 v[64:65], v[64:65], v[146:147] op_sel_hi:[1,0]
	v_sub_f32_e32 v109, v109, v147
	v_sub_f32_e32 v108, v108, v147
	v_sub_f32_e32 v107, v107, v147
	v_sub_f32_e32 v106, v106, v147
	v_sub_f32_e32 v105, v105, v147
	v_sub_f32_e32 v104, v104, v147
	v_sub_f32_e32 v103, v103, v147
	v_sub_f32_e32 v102, v102, v147
	v_sub_f32_e32 v101, v101, v147
	v_sub_f32_e32 v100, v100, v147
	v_sub_f32_e32 v99, v99, v147
	v_sub_f32_e32 v98, v98, v147
	v_sub_f32_e32 v97, v97, v147
	v_sub_f32_e32 v96, v96, v147
	v_sub_f32_e32 v95, v95, v147
	v_sub_f32_e32 v94, v94, v147
	v_sub_f32_e32 v93, v93, v147
	v_sub_f32_e32 v92, v92, v147
	v_sub_f32_e32 v91, v91, v147
	v_sub_f32_e32 v90, v90, v147
	v_sub_f32_e32 v89, v89, v147
	v_sub_f32_e32 v88, v88, v147
	v_sub_f32_e32 v87, v87, v147
	v_sub_f32_e32 v86, v86, v147
	v_sub_f32_e32 v85, v85, v147
	v_sub_f32_e32 v84, v84, v147
	v_sub_f32_e32 v83, v83, v147
	v_sub_f32_e32 v82, v82, v147
	v_sub_f32_e32 v81, v81, v147
	v_sub_f32_e32 v80, v80, v147

; #define LAS __attribute__((address_space(3)))
; #define MFMA32(a, b, c) __builtin_amdgcn_mfma_f32_32x32x16_bf16((a), (b), (c), 0, 0, 0)
; #define AT_ISSUE_K(jn) do { const int jc_ = (jn) < ntm1 ? (jn) : ntm1; const size_t ko_ = (size_t)jc_ * 8192; ks0 = *(const u32x4*)(bK1 + ko_ + koff); ks1 = *(const u32x4*)(bK2 + ko_ + koff); } while (0)
; __device__ __forceinline__ void at_pv_half(const LAS unsigned char* vp, const bf16x8 (&pf)[4], f32x16 (&O)[4], f32x16& L) {
;     bf16x8 va[8], vb[8];
; #pragma unroll
;     for (int e = 0; e < 2; ++e)
; #pragma unroll
;         for (int ks = 0; ks < 4; ++ks) va[e * 4 + ks] = *(const LAS bf16x8*)(vp + e * 32 * AT_ROWB + 32 * ks);
; #pragma unroll
;     for (int e = 0; e < 2; ++e)
; #pragma unroll
;         for (int ks = 0; ks < 4; ++ks) vb[e * 4 + ks] = *(const LAS bf16x8*)(vp + (2 + e) * 32 * AT_ROWB + 32 * ks);
;     const short one = (short)0x3F80; const bf16x8 ones = {one, one, one, one, one, one, one, one};
;     __builtin_amdgcn_sched_barrier(0);
;     __builtin_amdgcn_s_setprio(1);
; #pragma unroll
;     for (int ks = 0; ks < 4; ++ks) L = MFMA32(ones, pf[ks], L);
;     __builtin_amdgcn_sched_barrier(0);
; #pragma unroll
;     for (int ks = 0; ks < 4; ++ks) { O[0] = MFMA32(va[ks], pf[ks], O[0]); O[1] = MFMA32(va[4 + ks], pf[ks], O[1]); }
; #pragma unroll
;     for (int ks = 0; ks < 4; ++ks) { O[2] = MFMA32(vb[ks], pf[ks], O[2]); O[3] = MFMA32(vb[4 + ks], pf[ks], O[3]); }
;     __builtin_amdgcn_s_setprio(0);
; }
; __device__ __forceinline__ void attn_item(LAS unsigned char* lds, const bf16_t* Q, const bf16_t* Kb, const bf16_t* VT, bf16_t* aout, const float* subg, float lam, float omli, float kbound, int head, int qb) {
;     ...
;             __builtin_amdgcn_s_setprio(3);
;             { const int jc_ = (j + 1) < ntm1 ? (j + 1) : ntm1; const size_t vo_ = (size_t)jc_ * 16384; const char* pga = bV0 + vo_ + voff; const char* pgb = bV1 + vo_ + voff;
;               at_qk_half(online, act, stg + kfo, vs0, vs1, pga, pgb, qf, q, q0, kbase, hh, mrun, O, L, pf); }
;             __builtin_amdgcn_s_setprio(3);
;             AT_WRITE_K(j + 1);
;             __syncthreads();
;             __builtin_amdgcn_s_setprio(0);
;             AT_ISSUE_K(j + 2);
;             if (act) at_pv_half(stg + vfo, pf, O, L);
.LBB0_320:
	s_setprio 0
	s_setprio 3
	s_bitcmp1_b32 s56, 0
	s_cselect_b32 s55, 0x4800, 0
	s_waitcnt lgkmcnt(7)
	v_add_u32_e32 v96, s55, v213
	s_waitcnt vmcnt(3)
	ds_write_b128 v96, v[130:133]
	s_waitcnt vmcnt(2)
	ds_write_b128 v96, v[134:137] offset:9216
	s_waitcnt lgkmcnt(0)
	s_barrier
	s_setprio 0
	s_add_i32 s53, s53, 2
	s_min_i32 s58, s53, s41
	s_lshl_b64 s[60:61], s[58:59], 13
	v_lshl_add_u64 v[98:99], v[204:205], 0, s[60:61]
	v_lshl_add_u64 v[100:101], v[206:207], 0, s[60:61]
	global_load_dwordx4 v[130:133], v[98:99], off
	global_load_dwordx4 v[134:137], v[100:101], off
	s_andn2_b64 vcc, exec, s[0:1]
	s_cbranch_vccnz .LBB0_322
	v_add_u32_e32 v97, s54, v228
	ds_read_b128 v[98:101], v97 offset:36864
	ds_read_b128 v[150:153], v97 offset:41472
	ds_read_b128 v[166:169], v97 offset:46080
	ds_read_b128 v[234:237], v97 offset:50688
	ds_read_b128 v[102:105], v97 offset:36896
	ds_read_b128 v[154:157], v97 offset:41504
	ds_read_b128 v[170:173], v97 offset:46112
	ds_read_b128 v[238:241], v97 offset:50720
	ds_read_b128 v[106:109], v97 offset:36928
	ds_read_b128 v[158:161], v97 offset:41536
	ds_read_b128 v[176:179], v97 offset:46144
	ds_read_b128 v[242:245], v97 offset:50752
	ds_read_b128 v[146:149], v97 offset:36960
	ds_read_b128 v[162:165], v97 offset:41568
	ds_read_b128 v[230:233], v97 offset:46176
	ds_read_b128 v[246:249], v97 offset:50784
	s_setprio 1
	v_mfma_f32_16x16x32_bf16 v[64:67], v[76:79], v[80:83], v[64:67]
	v_mfma_f32_16x16x32_bf16 v[64:67], v[76:79], v[88:91], v[64:67]
	v_mfma_f32_16x16x32_bf16 v[64:67], v[76:79], v[84:87], v[64:67]
	v_mfma_f32_16x16x32_bf16 v[64:67], v[76:79], v[92:95], v[64:67]
	s_waitcnt lgkmcnt(15)
	v_mfma_f32_32x32x16_bf16 v[48:63], v[98:101], v[80:83], v[48:63]
	s_waitcnt lgkmcnt(14)
	v_mfma_f32_32x32x16_bf16 v[32:47], v[150:153], v[80:83], v[32:47]
	s_waitcnt lgkmcnt(13)
	v_mfma_f32_32x32x16_bf16 v[16:31], v[166:169], v[80:83], v[16:31]
	s_waitcnt lgkmcnt(12)
	v_mfma_f32_32x32x16_bf16 v[0:15], v[234:237], v[80:83], v[0:15]
	s_waitcnt lgkmcnt(11)
	v_mfma_f32_32x32x16_bf16 v[48:63], v[102:105], v[88:91], v[48:63]
	s_waitcnt lgkmcnt(10)
	v_mfma_f32_32x32x16_bf16 v[32:47], v[154:157], v[88:91], v[32:47]
	s_waitcnt lgkmcnt(9)
	v_mfma_f32_32x32x16_bf16 v[16:31], v[170:173], v[88:91], v[16:31]
	s_waitcnt lgkmcnt(8)
	v_mfma_f32_32x32x16_bf16 v[0:15], v[238:241], v[88:91], v[0:15]
	s_waitcnt lgkmcnt(7)
	v_mfma_f32_32x32x16_bf16 v[48:63], v[106:109], v[84:87], v[48:63]
	s_waitcnt lgkmcnt(6)
	v_mfma_f32_32x32x16_bf16 v[32:47], v[158:161], v[84:87], v[32:47]
	s_waitcnt lgkmcnt(5)
	v_mfma_f32_32x32x16_bf16 v[16:31], v[176:179], v[84:87], v[16:31]
	s_waitcnt lgkmcnt(4)
	v_mfma_f32_32x32x16_bf16 v[0:15], v[242:245], v[84:87], v[0:15]
	s_waitcnt lgkmcnt(3)
	v_mfma_f32_32x32x16_bf16 v[48:63], v[146:149], v[92:95], v[48:63]
	s_waitcnt lgkmcnt(2)
	v_mfma_f32_32x32x16_bf16 v[32:47], v[162:165], v[92:95], v[32:47]
	s_waitcnt lgkmcnt(1)
	v_mfma_f32_32x32x16_bf16 v[16:31], v[230:233], v[92:95], v[16:31]
	s_waitcnt lgkmcnt(0)
	v_mfma_f32_32x32x16_bf16 v[0:15], v[246:249], v[92:95], v[0:15]
	s_setprio 0

; __device__ __forceinline__ void attn_item(LAS unsigned char* lds, const bf16_t* Q, const bf16_t* Kb, const bf16_t* VT, bf16_t* aout, const float* subg, float lam, float omli, float kbound, int head, int qb) {
;     int tid_ = threadIdx.x; asm volatile("" : "+v"(tid_));
;     const int tid = tid_, lane = tid & 63, r = lane & 31, hh = lane >> 5; const int wid = __builtin_amdgcn_readfirstlane(tid >> 6);
;     const int comp = wid >> 2, qt = wid & 3; const int q0 = qb * 128 + qt * 32, q = q0 + r; const int nt = 2 * qb + 2;
;     bf16x8 qf[4];
;     { const bf16_t* Qp = Q + ((size_t)(head * 2 + comp) * S + q) * 64 + 8 * hh;
; #pragma unroll
;       for (int s = 0; s < 4; ++s) qf[s] = *(const bf16x8*)(Qp + 16 * s); }
;     const int srow = tid >> 3, sch = tid & 7;
;     const char* bK1 = (const char*)(Kb + (size_t)(head * 2 + 0) * S * 64); const char* bK2 = (const char*)(Kb + (size_t)(head * 2 + 1) * S * 64);
;     const char* bV0 = (const char*)(VT + (size_t)head * 256 * 128 * 64); const char* bV1 = bV0 + 8192;
;     const unsigned koff = srow * 128 + sch * 16, voff = koff;
;     const unsigned dK1 = srow * AT_ROWB + sch * 16, dK2 = AT_K2 + dK1, dV0 = AT_VOFF + dK1, dV1 = AT_VOFF + 64 * AT_ROWB + dK1;
;     u32x4 ks0 = *(const u32x4*)(bK1 + koff), ks1 = *(const u32x4*)(bK2 + koff), vs0 = *(const u32x4*)(bV0 + voff), vs1 = *(const u32x4*)(bV1 + voff);
;     *(LAS u32x4*)(lds + dK1) = ks0; *(LAS u32x4*)(lds + dK2) = ks1; *(LAS u32x4*)(lds + dV0) = vs0; *(LAS u32x4*)(lds + dV1) = vs1;
;     ks0 = *(const u32x4*)(bK1 + 8192 + koff); ks1 = *(const u32x4*)(bK2 + 8192 + koff);
;     asm volatile("" : "+v"(qf[0]), "+v"(qf[1]), "+v"(qf[2]), "+v"(qf[3]));
;     __syncthreads();
;     f32x16 O[4];
; #pragma unroll
;     for (int e = 0; e < 4; ++e)
; #pragma unroll
;         for (int i = 0; i < 16; ++i) O[e][i] = 0.f;
;     float qn2 = 0.f;
; #pragma unroll
;     for (int s = 0; s < 4; ++s)
; #pragma unroll
;         for (int e = 0; e < 8; ++e) { const float v = bf2f((bf16_t)qf[s][e]); qn2 += v * v; }
;     const float sbound = __builtin_sqrtf(half_swap_sum(qn2)) * kbound;
;     const bool online = __builtin_amdgcn_ballot_w64(!(sbound <= 100.f)) != 0ull;
;     float mrun = 0.f;
;     f32x16 L;
; #pragma unroll
;     for (int i = 0; i < 16; ++i) L[i] = 0.f;
;     bf16x8 pf[4];
; #pragma unroll
;     for (int i = 0; i < 4; ++i) pf[i] = (bf16x8){0, 0, 0, 0, 0, 0, 0, 0};
.LBB0_330:
	v_mov_b32_e32 v2, v182
	s_barrier
	s_lshl_b32 s0, s21, 7
	v_readfirstlane_b32 s26, v2
	s_ashr_i32 s24, s26, 8
	s_bfe_u32 s23, s26, 0x20006
	s_lshl_b32 s1, s23, 5
	s_add_i32 s4, s24, s22
	v_and_b32_e32 v227, 31, v2
	s_or_b32 s33, s1, s0
	s_ashr_i32 s5, s4, 31
	v_or_b32_e32 v202, s33, v227
	s_lshl_b32 s0, s21, 1
	s_lshl_b64 s[4:5], s[4:5], 21
	v_ashrrev_i32_e32 v203, 31, v202
	s_add_u32 s4, s11, s4
	v_bfe_u32 v226, v2, 5, 1
	s_addc_u32 s5, s12, s5
	v_lshlrev_b64 v[0:1], 7, v[202:203]
	v_lshl_add_u64 v[0:1], s[4:5], 0, v[0:1]
	v_lshlrev_b32_e32 v112, 4, v226
	v_lshl_add_u64 v[16:17], v[0:1], 0, v[112:113]
	v_lshlrev_b32_e32 v0, 4, v2
	v_ashrrev_i32_e32 v19, 3, v2
	v_and_b32_e32 v18, 0x70, v0
	v_lshl_or_b32 v20, v19, 7, v18
	global_load_dwordx4 v[0:3], v20, s[8:9]
	global_load_dwordx4 v[4:7], v20, s[38:39]
	global_load_dwordx4 v[8:11], v20, s[42:43]
	global_load_dwordx4 v[12:15], v20, s[46:47]
	global_load_dwordx4 v[114:117], v[16:17], off offset:96
	global_load_dwordx4 v[118:121], v[16:17], off offset:64
	global_load_dwordx4 v[122:125], v[16:17], off offset:32
	global_load_dwordx4 v[126:129], v[16:17], off
	global_load_dwordx4 v[130:133], v20, s[50:51]
	global_load_dwordx4 v[134:137], v20, s[62:63]
	v_mad_u64_u32 v[212:213], s[4:5], v19, s66, v[18:19]
	v_add_u32_e32 v213, 0, v212
	v_mov_b32_e32 v21, v113
	v_lshl_add_u64 v[204:205], s[8:9], 0, v[20:21]
	v_lshl_add_u64 v[206:207], s[38:39], 0, v[20:21]
	v_lshl_add_u64 v[208:209], s[42:43], 0, v[20:21]
	v_lshl_add_u64 v[210:211], s[46:47], 0, v[20:21]
	s_mul_i32 s1, s24, 0x2400
	v_mad_u32_u24 v228, v227, s66, v112
	v_add_u32_e32 v229, s1, v228
	s_waitcnt vmcnt(9)
	ds_write_b128 v213, v[0:3]
	s_waitcnt vmcnt(8)
	ds_write_b128 v213, v[4:7] offset:9216
	s_waitcnt vmcnt(7)
	ds_write_b128 v213, v[8:11] offset:36864
	s_waitcnt vmcnt(6)
	ds_write_b128 v213, v[12:15] offset:46080
	s_waitcnt vmcnt(2)
	s_nop 0
	v_and_b32_e32 v7, 0xffff0000, v126
	v_lshlrev_b32_e32 v6, 16, v126
	v_mul_f32_e32 v7, v7, v7
	v_lshlrev_b32_e32 v8, 16, v127
	v_fmac_f32_e32 v7, v6, v6
	v_and_b32_e32 v9, 0xffff0000, v127
	v_fmac_f32_e32 v7, v8, v8
	v_lshlrev_b32_e32 v10, 16, v128
	v_fmac_f32_e32 v7, v9, v9
	v_and_b32_e32 v11, 0xffff0000, v128
	v_fmac_f32_e32 v7, v10, v10
	v_lshlrev_b32_e32 v12, 16, v129
	v_fmac_f32_e32 v7, v11, v11
	v_and_b32_e32 v13, 0xffff0000, v129
	v_fmac_f32_e32 v7, v12, v12
	v_lshlrev_b32_e32 v14, 16, v122
	v_fmac_f32_e32 v7, v13, v13
	v_and_b32_e32 v15, 0xffff0000, v122
	v_fmac_f32_e32 v7, v14, v14
	v_lshlrev_b32_e32 v16, 16, v123
	v_fmac_f32_e32 v7, v15, v15
	v_and_b32_e32 v17, 0xffff0000, v123
	v_fmac_f32_e32 v7, v16, v16
	v_lshlrev_b32_e32 v18, 16, v124
	v_fmac_f32_e32 v7, v17, v17
	v_and_b32_e32 v19, 0xffff0000, v124
	v_fmac_f32_e32 v7, v18, v18
	v_lshlrev_b32_e32 v20, 16, v125
	v_fmac_f32_e32 v7, v19, v19
	v_and_b32_e32 v21, 0xffff0000, v125
	v_fmac_f32_e32 v7, v20, v20
	v_lshlrev_b32_e32 v22, 16, v118
	v_fmac_f32_e32 v7, v21, v21
	v_and_b32_e32 v23, 0xffff0000, v118
	v_fmac_f32_e32 v7, v22, v22
	v_lshlrev_b32_e32 v24, 16, v119
	v_fmac_f32_e32 v7, v23, v23
	v_and_b32_e32 v25, 0xffff0000, v119
	v_fmac_f32_e32 v7, v24, v24
	v_lshlrev_b32_e32 v26, 16, v120
	v_fmac_f32_e32 v7, v25, v25
	v_and_b32_e32 v27, 0xffff0000, v120
	v_fmac_f32_e32 v7, v26, v26
	v_lshlrev_b32_e32 v28, 16, v121
	v_fmac_f32_e32 v7, v27, v27
	v_and_b32_e32 v29, 0xffff0000, v121
	v_fmac_f32_e32 v7, v28, v28
	v_lshlrev_b32_e32 v30, 16, v114
	v_fmac_f32_e32 v7, v29, v29
	v_and_b32_e32 v31, 0xffff0000, v114
	v_and_b32_e32 v1, 0xffff0000, v115
	v_lshlrev_b32_e32 v0, 16, v115
	v_fmac_f32_e32 v7, v30, v30
	v_pk_mul_f32 v[0:1], v[0:1], v[0:1]
	v_fmac_f32_e32 v7, v31, v31
	v_and_b32_e32 v3, 0xffff0000, v116
	v_lshlrev_b32_e32 v2, 16, v116
	v_add_f32_e32 v0, v0, v7
	v_pk_mul_f32 v[2:3], v[2:3], v[2:3]
	v_add_f32_e32 v0, v1, v0
	v_and_b32_e32 v5, 0xffff0000, v117
	v_lshlrev_b32_e32 v4, 16, v117
	v_add_f32_e32 v0, v2, v0
	v_pk_mul_f32 v[4:5], v[4:5], v[4:5]
	v_add_f32_e32 v0, v3, v0
	v_add_f32_e32 v0, v4, v0
	v_add_f32_e32 v0, v5, v0
	v_mov_b32_e32 v1, v0
	s_nop 1
	v_permlane32_swap_b32_e32 v0, v1
	v_add_f32_e32 v0, v0, v1
	v_mul_f32_e32 v1, 0x4f800000, v0
	v_cmp_gt_f32_e32 vcc, s67, v0
	s_waitcnt lgkmcnt(0)
	s_barrier
	v_cndmask_b32_e32 v0, v0, v1, vcc
	v_sqrt_f32_e32 v1, v0
	s_nop 0
	v_add_u32_e32 v2, -1, v1
	v_add_u32_e32 v3, 1, v1
	v_fma_f32 v4, -v2, v1, v0
	v_fma_f32 v5, -v3, v1, v0
	v_cmp_ge_f32_e64 s[4:5], 0, v4
	s_nop 1
	v_cndmask_b32_e64 v1, v1, v2, s[4:5]
	v_cmp_lt_f32_e64 s[4:5], 0, v5
	s_nop 1
	v_cndmask_b32_e64 v1, v1, v3, s[4:5]
	v_mul_f32_e32 v2, 0x37800000, v1
	v_cndmask_b32_e32 v1, v1, v2, vcc
	v_cmp_class_f32_e32 vcc, v0, v219
	s_nop 1
	v_cndmask_b32_e32 v0, v1, v0, vcc
	v_mul_f32_e32 v0, v225, v0
	v_cmp_nge_f32_e32 vcc, s68, v0
	s_cmp_lg_u64 vcc, 0
	s_cselect_b64 s[8:9], -1, 0
	s_or_b32 s21, s33, 31
	s_or_b32 s22, s0, 1
	s_cmpk_lt_u32 s26, 0x100
	s_cselect_b64 s[4:5], -1, 0
	s_mov_b64 s[0:1], -1
	s_and_b64 vcc, exec, s[4:5]
	s_cbranch_vccnz .LBB0_348
	s_cmp_lt_i32 s20, 0
	s_cbranch_scc1 .LBB0_344
; #define LAS __attribute__((address_space(3)))
; __device__ __forceinline__ float bf2f(bf16_t v) { return __uint_as_float(((unsigned)v) << 16); }
; #define MFMA32(a, b, c) __builtin_amdgcn_mfma_f32_32x32x16_bf16((a), (b), (c), 0, 0, 0)
; __device__ __forceinline__ void at_pv_half(const LAS unsigned char* vp, const bf16x8 (&pf)[4], f32x16 (&O)[4], f32x16& L) {
;     bf16x8 va[8], vb[8];
; #pragma unroll
;     for (int e = 0; e < 2; ++e)
; #pragma unroll
;         for (int ks = 0; ks < 4; ++ks) va[e * 4 + ks] = *(const LAS bf16x8*)(vp + e * 32 * AT_ROWB + 32 * ks);
; #pragma unroll
;     for (int e = 0; e < 2; ++e)
; #pragma unroll
;         for (int ks = 0; ks < 4; ++ks) vb[e * 4 + ks] = *(const LAS bf16x8*)(vp + (2 + e) * 32 * AT_ROWB + 32 * ks);
;     const short one = (short)0x3F80; const bf16x8 ones = {one, one, one, one, one, one, one, one};
;     __builtin_amdgcn_sched_barrier(0);
;     __builtin_amdgcn_s_setprio(1);
; #pragma unroll
;     for (int ks = 0; ks < 4; ++ks) L = MFMA32(ones, pf[ks], L);
;     __builtin_amdgcn_sched_barrier(0);
; #pragma unroll
;     for (int ks = 0; ks < 4; ++ks) { O[0] = MFMA32(va[ks], pf[ks], O[0]); O[1] = MFMA32(va[4 + ks], pf[ks], O[1]); }
; #pragma unroll
;     for (int ks = 0; ks < 4; ++ks) { O[2] = MFMA32(vb[ks], pf[ks], O[2]); O[3] = MFMA32(vb[4 + ks], pf[ks], O[3]); }
;     __builtin_amdgcn_s_setprio(0);
; }
; __device__ __forceinline__ void attn_item(LAS unsigned char* lds, const bf16_t* Q, const bf16_t* Kb, const bf16_t* VT, bf16_t* aout, const float* subg, float lam, float omli, float kbound, int head, int qb) {
;     ...
;     f32x16 O[4];
; #pragma unroll
;     for (int e = 0; e < 4; ++e)
; #pragma unroll
;         for (int i = 0; i < 16; ++i) O[e][i] = 0.f;
;     float qn2 = 0.f;
; #pragma unroll
;     for (int s = 0; s < 4; ++s)
; #pragma unroll
;         for (int e = 0; e < 8; ++e) { const float v = bf2f((bf16_t)qf[s][e]); qn2 += v * v; }
;     const float sbound = __builtin_sqrtf(half_swap_sum(qn2)) * kbound;
;     const bool online = __builtin_amdgcn_ballot_w64(!(sbound <= 100.f)) != 0ull;
;     float mrun = 0.f;
;     f32x16 L;
; #pragma unroll
;     for (int i = 0; i < 16; ++i) L[i] = 0.f;
;     bf16x8 pf[4];
; #pragma unroll
;     for (int i = 0; i < 4; ++i) pf[i] = (bf16x8){0, 0, 0, 0, 0, 0, 0, 0};
	s_lshl_b32 s0, s20, 1
	s_and_b32 s0, s0, -4
	s_or_b32 s0, s0, s19
	v_mov_b32_e32 v14, v113
	v_mov_b32_e32 v15, v113
	s_add_i32 s0, s0, 2
	v_mov_b32_e32 v0, v113
	v_mov_b32_e32 v1, v113
	v_mov_b32_e32 v2, v113
	v_mov_b32_e32 v3, v113
	v_mov_b32_e32 v4, v113
	v_mov_b32_e32 v5, v113
	v_mov_b32_e32 v6, v113
	v_mov_b32_e32 v7, v113
	v_mov_b32_e32 v8, v113
	v_mov_b32_e32 v9, v113
	v_mov_b32_e32 v10, v113
	v_mov_b32_e32 v11, v113
	v_mov_b32_e32 v12, v113
	v_mov_b32_e32 v13, v113
	v_mov_b64_e32 v[30:31], v[14:15]
	v_mov_b64_e32 v[46:47], v[14:15]
	v_mov_b64_e32 v[62:63], v[14:15]
	v_mov_b64_e32 v[78:79], v[14:15]
	s_waitcnt vmcnt(0)
	v_mov_b64_e32 v[140:141], v[136:137]
	v_mov_b64_e32 v[144:145], v[132:133]
	v_add_u32_e32 v230, 0, v229
	v_lshlrev_b32_e32 v231, 2, v226
	s_max_i32 s0, s0, 1
	s_mov_b32 s39, 0
	v_mov_b32_e32 v214, 0
	s_mov_b32 s1, 63
	v_mov_b32_e32 v92, 0
	v_mov_b32_e32 v93, 0
	v_mov_b32_e32 v94, 0
	v_mov_b32_e32 v95, 0
	v_mov_b32_e32 v84, 0
	v_mov_b32_e32 v85, 0
	v_mov_b32_e32 v86, 0
	v_mov_b32_e32 v87, 0
	v_mov_b32_e32 v88, 0
	v_mov_b32_e32 v89, 0
	v_mov_b32_e32 v90, 0
	v_mov_b32_e32 v91, 0
	v_mov_b32_e32 v80, 0
	v_mov_b32_e32 v81, 0
	v_mov_b32_e32 v82, 0
	v_mov_b32_e32 v83, 0
	v_mov_b64_e32 v[28:29], v[12:13]
	v_mov_b64_e32 v[26:27], v[10:11]
	v_mov_b64_e32 v[24:25], v[8:9]
	v_mov_b64_e32 v[22:23], v[6:7]
	v_mov_b64_e32 v[20:21], v[4:5]
	v_mov_b64_e32 v[18:19], v[2:3]
	v_mov_b64_e32 v[16:17], v[0:1]
	v_mov_b64_e32 v[44:45], v[12:13]
	v_mov_b64_e32 v[42:43], v[10:11]
	v_mov_b64_e32 v[40:41], v[8:9]
	v_mov_b64_e32 v[38:39], v[6:7]
	v_mov_b64_e32 v[36:37], v[4:5]
	v_mov_b64_e32 v[34:35], v[2:3]
	v_mov_b64_e32 v[32:33], v[0:1]
	v_mov_b64_e32 v[60:61], v[12:13]
	v_mov_b64_e32 v[58:59], v[10:11]
	v_mov_b64_e32 v[56:57], v[8:9]
	v_mov_b64_e32 v[54:55], v[6:7]
	v_mov_b64_e32 v[52:53], v[4:5]
	v_mov_b64_e32 v[50:51], v[2:3]
	v_mov_b64_e32 v[48:49], v[0:1]
	v_mov_b64_e32 v[76:77], v[12:13]
	v_mov_b64_e32 v[74:75], v[10:11]
	v_mov_b64_e32 v[72:73], v[8:9]
	v_mov_b64_e32 v[70:71], v[6:7]
	v_mov_b64_e32 v[68:69], v[4:5]
	v_mov_b64_e32 v[66:67], v[2:3]
	v_mov_b64_e32 v[64:65], v[0:1]
	v_mov_b64_e32 v[138:139], v[134:135]
	v_mov_b64_e32 v[142:143], v[130:131]
	s_mov_b32 vcc_lo, 0xf0f00f0f
	s_mov_b32 vcc_hi, 0xf0f00f0f
	v_mov_b32_e32 v77, s52
	s_nop 1
	v_cndmask_b32_e32 v76, 0, v77, vcc
	v_mov_b32_e32 v77, v76
	v_mov_b32_e32 v78, v76
	v_mov_b32_e32 v79, v76
.LBB0_333:
	s_add_i32 s38, s39, 1
	s_bitcmp1_b32 s38, 0
	s_cselect_b32 s42, 0x4800, 0
	s_min_i32 s58, s38, s22
	s_lshl_b64 s[40:41], s[58:59], 14
	v_lshl_add_u64 v[96:97], v[208:209], 0, s[40:41]
	v_lshl_add_u64 v[98:99], v[210:211], 0, s[40:41]
	global_load_dwordx4 v[146:149], v[96:97], off
	global_load_dwordx4 v[150:153], v[98:99], off
	s_add_i32 s40, s42, 0
	s_cmp_eq_u32 s39, 0
	s_cselect_b64 s[42:43], -1, 0
	s_add_i32 s41, s1, 0xffffff81
	s_cmp_gt_i32 s41, s21
	s_cselect_b64 s[44:45], -1, 0
	s_or_b64 s[42:43], s[42:43], s[44:45]
	s_and_b64 vcc, exec, s[42:43]
	s_cbranch_vccnz .LBB0_335
	v_add_u32_e32 v244, s40, v228
	ds_read_b128 v[96:99], v244 offset:36864
	ds_read_b128 v[154:157], v244 offset:41472
	ds_read_b128 v[170:173], v244 offset:46080
	ds_read_b128 v[232:235], v244 offset:50688
	ds_read_b128 v[100:103], v244 offset:36896
	ds_read_b128 v[158:161], v244 offset:41504
	ds_read_b128 v[174:177], v244 offset:46112
	ds_read_b128 v[236:239], v244 offset:50720
	ds_read_b128 v[104:107], v244 offset:36928
	ds_read_b128 v[162:165], v244 offset:41536
	ds_read_b128 v[178:181], v244 offset:46144
	ds_read_b128 v[240:243], v244 offset:50752
	ds_read_b128 v[108:111], v244 offset:36960
	ds_read_b128 v[166:169], v244 offset:41568
	ds_read_b128 v[184:187], v244 offset:46176
	ds_read_b128 v[244:247], v244 offset:50784
	s_setprio 1
	v_mfma_f32_16x16x32_bf16 v[64:67], v[76:79], v[80:83], v[64:67]
	v_mfma_f32_16x16x32_bf16 v[64:67], v[76:79], v[88:91], v[64:67]
	v_mfma_f32_16x16x32_bf16 v[64:67], v[76:79], v[84:87], v[64:67]
	v_mfma_f32_16x16x32_bf16 v[64:67], v[76:79], v[92:95], v[64:67]
	s_waitcnt lgkmcnt(15)
	v_mfma_f32_32x32x16_bf16 v[48:63], v[96:99], v[80:83], v[48:63]
	s_waitcnt lgkmcnt(14)
	v_mfma_f32_32x32x16_bf16 v[32:47], v[154:157], v[80:83], v[32:47]
	s_waitcnt lgkmcnt(13)
	v_mfma_f32_32x32x16_bf16 v[16:31], v[170:173], v[80:83], v[16:31]
	s_waitcnt lgkmcnt(12)
	v_mfma_f32_32x32x16_bf16 v[0:15], v[232:235], v[80:83], v[0:15]
	s_waitcnt lgkmcnt(11)
	v_mfma_f32_32x32x16_bf16 v[48:63], v[100:103], v[88:91], v[48:63]
	s_waitcnt lgkmcnt(10)
	v_mfma_f32_32x32x16_bf16 v[32:47], v[158:161], v[88:91], v[32:47]
	s_waitcnt lgkmcnt(9)
	v_mfma_f32_32x32x16_bf16 v[16:31], v[174:177], v[88:91], v[16:31]
	s_waitcnt lgkmcnt(8)
	v_mfma_f32_32x32x16_bf16 v[0:15], v[236:239], v[88:91], v[0:15]
	s_waitcnt lgkmcnt(7)
	v_mfma_f32_32x32x16_bf16 v[48:63], v[104:107], v[84:87], v[48:63]
	s_waitcnt lgkmcnt(6)
	v_mfma_f32_32x32x16_bf16 v[32:47], v[162:165], v[84:87], v[32:47]
	s_waitcnt lgkmcnt(5)
	v_mfma_f32_32x32x16_bf16 v[16:31], v[178:181], v[84:87], v[16:31]
	s_waitcnt lgkmcnt(4)
	v_mfma_f32_32x32x16_bf16 v[0:15], v[240:243], v[84:87], v[0:15]
	s_waitcnt lgkmcnt(3)
	v_mfma_f32_32x32x16_bf16 v[48:63], v[108:111], v[92:95], v[48:63]
	s_waitcnt lgkmcnt(2)
	v_mfma_f32_32x32x16_bf16 v[32:47], v[166:169], v[92:95], v[32:47]
	s_waitcnt lgkmcnt(1)
	v_mfma_f32_32x32x16_bf16 v[16:31], v[184:187], v[92:95], v[16:31]
	s_waitcnt lgkmcnt(0)
	v_mfma_f32_32x32x16_bf16 v[0:15], v[244:247], v[92:95], v[0:15]
	s_setprio 0
; #define LAS __attribute__((address_space(3)))
; #define MFMA32(a, b, c) __builtin_amdgcn_mfma_f32_32x32x16_bf16((a), (b), (c), 0, 0, 0)
; #define AT_ISSUE_V(jn) do { const int jc_ = (jn) < ntm1 ? (jn) : ntm1; const size_t vo_ = (size_t)jc_ * 16384; vs0 = *(const u32x4*)(bV0 + vo_ + voff); vs1 = *(const u32x4*)(bV1 + vo_ + voff); } while (0)
; #define AT_WRITE_K(jn) do { LAS unsigned char* n_ = lds + ((jn) & 1) * AT_KST; *(LAS u32x4*)(n_ + dK1) = ks0; *(LAS u32x4*)(n_ + dK2) = ks1; } while (0)
; __device__ __forceinline__ void at_qk_half(const bool ONLINE, const bool act, const LAS unsigned char* kp, u32x4& pfa, u32x4& pfb, const char* pga, const char* pgb, const bf16x8 (&qf)[4], int q, int q0, int kbase, int hh, float& mrun, f32x16 (&O)[4], f32x16& L, bf16x8 (&pf)[4]) {
;     __builtin_amdgcn_s_setprio(3);
;     bf16x8 kf[8];
; #pragma unroll
;     for (int s = 0; s < 4; ++s) { kf[2 * s] = *(const LAS bf16x8*)(kp + 32 * s); kf[2 * s + 1] = *(const LAS bf16x8*)(kp + 32 * AT_ROWB + 32 * s); }
;     __builtin_amdgcn_sched_barrier(0);
;     pfa = *(const u32x4*)pga; pfb = *(const u32x4*)pgb;
;     __builtin_amdgcn_sched_barrier(0);
;     if (!act) { __builtin_amdgcn_s_setprio(0); return; }
;     f32x16 s0, s1;
; #pragma unroll
;     for (int i = 0; i < 16; ++i) { s0[i] = 0.f; s1[i] = 0.f; }
; #pragma unroll
;     for (int s = 0; s < 4; ++s) { s0 = MFMA32(kf[2 * s], qf[s], s0); s1 = MFMA32(kf[2 * s + 1], qf[s], s1); }
; __device__ __forceinline__ void attn_item(LAS unsigned char* lds, const bf16_t* Q, const bf16_t* Kb, const bf16_t* VT, bf16_t* aout, const float* subg, float lam, float omli, float kbound, int head, int qb) {
;     ...
;             const LAS unsigned char* stg = lds + (j & 1) * AT_KST; const LAS unsigned char* pst = lds + ((j + 1) & 1) * AT_KST; const int kbase = j * 64;
;             AT_ISSUE_V(j + 1);
;             if (j > 0 && kbase - 64 <= qmax) at_pv_half(pst + vfo, pf, O, L);
;             AT_WRITE_K(j + 1);
;             __syncthreads();
;             __builtin_amdgcn_s_setprio(3);
;             { const int jc_ = (j + 2) < ntm1 ? (j + 2) : ntm1; const size_t ko_ = (size_t)jc_ * 8192; const char* pga = bK1 + ko_ + koff; const char* pgb = bK2 + ko_ + koff;
;               at_qk_half(online, kbase <= qmax, stg + kfo, ks0, ks1, pga, pgb, qf, q, q0, kbase, hh, mrun, O, L, pf); }
.LBB0_335:
	s_bitcmp1_b32 s39, 0
	v_add_u32_e32 v232, s40, v212
	s_cselect_b32 s42, 0x4800, 0
	s_sub_i32 s43, s1, 63
	s_waitcnt vmcnt(3)
	ds_write_b128 v232, v[142:145]
	s_waitcnt vmcnt(2)
	ds_write_b128 v232, v[138:141] offset:9216
	s_waitcnt lgkmcnt(0)
	s_barrier
	s_setprio 3
	s_add_i32 s39, s39, 2
	s_min_i32 s58, s39, s22
	s_lshl_b64 s[40:41], s[58:59], 13
	v_lshl_add_u64 v[100:101], v[204:205], 0, s[40:41]
	v_lshl_add_u64 v[102:103], v[206:207], 0, s[40:41]
	s_cmp_gt_i32 s43, s21
	v_add_u32_e32 v104, s42, v230
	s_setprio 3
	ds_read_b128 v[96:99], v104
	ds_read_b128 v[166:169], v104 offset:32
	ds_read_b128 v[162:165], v104 offset:64
	ds_read_b128 v[154:157], v104 offset:96
	ds_read_b128 v[178:181], v104 offset:4608
	ds_read_b128 v[170:173], v104 offset:4640
	ds_read_b128 v[174:177], v104 offset:4672
	ds_read_b128 v[158:161], v104 offset:4704
	global_load_dwordx4 v[142:145], v[100:101], off
	global_load_dwordx4 v[138:141], v[102:103], off
	s_cbranch_scc1 .LBB0_342
	s_cmp_le_i32 s1, s33
	s_cbranch_scc0 .Lmy_slow3
	s_andn2_b64 vcc, exec, s[8:9]
	s_cbranch_vccz .Lmy_slow3
	s_waitcnt lgkmcnt(7)
	v_mfma_f32_32x32x16_bf16 v[96:111], v[96:99], v[126:129], 0
	s_waitcnt lgkmcnt(6)
	v_mfma_f32_32x32x16_bf16 v[96:111], v[166:169], v[122:125], v[96:111]
	s_waitcnt lgkmcnt(5)
	v_mfma_f32_32x32x16_bf16 v[96:111], v[162:165], v[118:121], v[96:111]
	s_waitcnt lgkmcnt(4)
	v_mfma_f32_32x32x16_bf16 v[96:111], v[154:157], v[114:117], v[96:111]
	s_waitcnt lgkmcnt(3)
	v_mfma_f32_32x32x16_bf16 v[80:95], v[178:181], v[126:129], 0
	s_waitcnt lgkmcnt(2)
	v_mfma_f32_32x32x16_bf16 v[80:95], v[170:173], v[122:125], v[80:95]
	s_nop 3
	v_exp_f32_e32 v96, v96
	v_exp_f32_e32 v97, v97
	v_exp_f32_e32 v98, v98
	v_exp_f32_e32 v99, v99
	s_waitcnt lgkmcnt(1)
	v_mfma_f32_32x32x16_bf16 v[80:95], v[174:177], v[118:121], v[80:95]
	v_exp_f32_e32 v100, v100
	v_exp_f32_e32 v101, v101
	v_exp_f32_e32 v102, v102
	v_exp_f32_e32 v103, v103
	s_waitcnt lgkmcnt(0)
	v_mfma_f32_32x32x16_bf16 v[80:95], v[158:161], v[114:117], v[80:95]
	s_setprio 0
	v_exp_f32_e32 v104, v104
	v_exp_f32_e32 v105, v105
	v_exp_f32_e32 v106, v106
	v_exp_f32_e32 v107, v107
	v_exp_f32_e32 v108, v108
	v_exp_f32_e32 v109, v109
	v_exp_f32_e32 v110, v110
	v_exp_f32_e32 v111, v111
	s_nop 3
	v_exp_f32_e32 v154, v80
	v_exp_f32_e32 v155, v81
	v_exp_f32_e32 v156, v82
	v_exp_f32_e32 v157, v83
	v_exp_f32_e32 v158, v84
	v_exp_f32_e32 v159, v85
	v_exp_f32_e32 v160, v86
	v_exp_f32_e32 v161, v87
	v_exp_f32_e32 v162, v88
	v_exp_f32_e32 v163, v89
	v_exp_f32_e32 v164, v90
	v_exp_f32_e32 v165, v91
	v_exp_f32_e32 v166, v92
	v_exp_f32_e32 v167, v93
	v_exp_f32_e32 v168, v94
	v_exp_f32_e32 v169, v95
	v_cvt_pk_bf16_f32 v80, v96, v97
	v_cvt_pk_bf16_f32 v81, v98, v99
	v_cvt_pk_bf16_f32 v82, v100, v101
	v_cvt_pk_bf16_f32 v83, v102, v103
	v_cvt_pk_bf16_f32 v84, v154, v155
	v_cvt_pk_bf16_f32 v85, v156, v157
	v_cvt_pk_bf16_f32 v86, v158, v159
	v_cvt_pk_bf16_f32 v87, v160, v161
	v_cvt_pk_bf16_f32 v88, v104, v105
	v_cvt_pk_bf16_f32 v89, v106, v107
	v_cvt_pk_bf16_f32 v90, v108, v109
	v_cvt_pk_bf16_f32 v91, v110, v111
	v_cvt_pk_bf16_f32 v92, v162, v163
	v_cvt_pk_bf16_f32 v93, v164, v165
	v_cvt_pk_bf16_f32 v94, v166, v167
	v_cvt_pk_bf16_f32 v95, v168, v169
	s_branch .LBB0_342

; __device__ __forceinline__ float half_swap_max(float v) { auto rr = __builtin_amdgcn_permlane32_swap(__float_as_uint(v), __float_as_uint(v), false, false); return fmaxf(__uint_as_float(rr[0]), __uint_as_float(rr[1])); }
; __device__ __forceinline__ float at_max3(float a, float b, float c) { float r; asm("v_max3_f32 %0, %1, %2, %3" : "=v"(r) : "v"(a), "v"(b), "v"(c)); return r; }
; __device__ __forceinline__ void at_qk_half(const bool ONLINE, const bool act, const LAS unsigned char* kp, u32x4& pfa, u32x4& pfb, const char* pga, const char* pgb, const bf16x8 (&qf)[4], int q, int q0, int kbase, int hh, float& mrun, f32x16 (&O)[4], f32x16& L, bf16x8 (&pf)[4]) {
;     ...
;     if (ONLINE) {
; #pragma unroll
;         for (int i = 0; i < 16; ++i) { s0[i] -= mrun; s1[i] -= mrun; }
;         float mx = fmaxf(s0[0], s1[0]);
; #pragma unroll
;         for (int i = 1; i < 16; ++i) mx = at_max3(mx, s0[i], s1[i]);
;         mx = half_swap_max(mx);
;         if (__builtin_amdgcn_ballot_w64(mx > 8.f) != 0ull) {
;             const float d = fmaxf(mx, 0.f); const float alpha = __builtin_amdgcn_exp2f(-d); mrun += d;
; #pragma unroll
;             for (int e = 0; e < 4; ++e)
; #pragma unroll
;                 for (int i = 0; i < 16; ++i) O[e][i] *= alpha;
; #pragma unroll
;             for (int i = 0; i < 16; ++i) { L[i] *= alpha; s0[i] -= d; s1[i] -= d; }
;         }
;     }
.LBB0_338:
	s_andn2_b64 vcc, exec, s[8:9]
	s_cbranch_vccnz .LBB0_341
	s_nop 4
	v_pk_add_f32 v[96:97], v[96:97], v[214:215] op_sel_hi:[1,0] neg_lo:[0,1] neg_hi:[0,1]
	s_nop 0
	v_pk_add_f32 v[80:81], v[80:81], v[214:215] op_sel_hi:[1,0] neg_lo:[0,1] neg_hi:[0,1]
	v_pk_add_f32 v[98:99], v[98:99], v[214:215] op_sel_hi:[1,0] neg_lo:[0,1] neg_hi:[0,1]
	v_max_f32_e32 v154, v96, v80
	v_max3_f32 v154, v154, v97, v81
	v_pk_add_f32 v[82:83], v[82:83], v[214:215] op_sel_hi:[1,0] neg_lo:[0,1] neg_hi:[0,1]
	v_pk_add_f32 v[100:101], v[100:101], v[214:215] op_sel_hi:[1,0] neg_lo:[0,1] neg_hi:[0,1]
	v_max3_f32 v154, v154, v98, v82
	v_pk_add_f32 v[84:85], v[84:85], v[214:215] op_sel_hi:[1,0] neg_lo:[0,1] neg_hi:[0,1]
	v_max3_f32 v154, v154, v99, v83
	v_pk_add_f32 v[102:103], v[102:103], v[214:215] op_sel_hi:[1,0] neg_lo:[0,1] neg_hi:[0,1]
	v_max3_f32 v154, v154, v100, v84
	v_pk_add_f32 v[86:87], v[86:87], v[214:215] op_sel_hi:[1,0] neg_lo:[0,1] neg_hi:[0,1]
	v_max3_f32 v154, v154, v101, v85
	v_pk_add_f32 v[104:105], v[104:105], v[214:215] op_sel_hi:[1,0] neg_lo:[0,1] neg_hi:[0,1]
	v_max3_f32 v154, v154, v102, v86
	v_pk_add_f32 v[88:89], v[88:89], v[214:215] op_sel_hi:[1,0] neg_lo:[0,1] neg_hi:[0,1]
	v_max3_f32 v154, v154, v103, v87
	v_pk_add_f32 v[106:107], v[106:107], v[214:215] op_sel_hi:[1,0] neg_lo:[0,1] neg_hi:[0,1]
	v_max3_f32 v154, v154, v104, v88
	v_pk_add_f32 v[90:91], v[90:91], v[214:215] op_sel_hi:[1,0] neg_lo:[0,1] neg_hi:[0,1]
	v_max3_f32 v154, v154, v105, v89
	v_pk_add_f32 v[108:109], v[108:109], v[214:215] op_sel_hi:[1,0] neg_lo:[0,1] neg_hi:[0,1]
	v_max3_f32 v154, v154, v106, v90
	v_pk_add_f32 v[92:93], v[92:93], v[214:215] op_sel_hi:[1,0] neg_lo:[0,1] neg_hi:[0,1]
	v_max3_f32 v154, v154, v107, v91
	v_pk_add_f32 v[110:111], v[110:111], v[214:215] op_sel_hi:[1,0] neg_lo:[0,1] neg_hi:[0,1]
	v_max3_f32 v154, v154, v108, v92
	v_pk_add_f32 v[94:95], v[94:95], v[214:215] op_sel_hi:[1,0] neg_lo:[0,1] neg_hi:[0,1]
	v_max3_f32 v154, v154, v109, v93
	s_nop 0
	v_max3_f32 v154, v154, v110, v94
	s_nop 0
	v_max3_f32 v154, v154, v111, v95
	s_nop 0
	v_mov_b32_e32 v155, v154
	s_nop 1
	v_permlane32_swap_b32_e32 v154, v155
	v_max_f32_e32 v155, v155, v155
	v_max_f32_e32 v154, v154, v154
	v_max_f32_e32 v154, v154, v155
	v_cmp_lt_f32_e32 vcc, s25, v154
	s_cbranch_vccz .LBB0_341
	v_max_f32_e32 v154, v154, v154
	v_max_f32_e32 v155, 0, v154
	v_exp_f32_e64 v154, -v155
	v_add_f32_e32 v214, v214, v155
	v_sub_f32_e32 v111, v111, v155
	v_sub_f32_e32 v110, v110, v155
	v_pk_mul_f32 v[62:63], v[62:63], v[154:155] op_sel_hi:[1,0]
	v_pk_mul_f32 v[60:61], v[60:61], v[154:155] op_sel_hi:[1,0]
	v_pk_mul_f32 v[58:59], v[58:59], v[154:155] op_sel_hi:[1,0]
	v_pk_mul_f32 v[56:57], v[56:57], v[154:155] op_sel_hi:[1,0]
	v_pk_mul_f32 v[54:55], v[54:55], v[154:155] op_sel_hi:[1,0]
	v_pk_mul_f32 v[52:53], v[52:53], v[154:155] op_sel_hi:[1,0]
	v_pk_mul_f32 v[50:51], v[50:51], v[154:155] op_sel_hi:[1,0]
	v_pk_mul_f32 v[48:49], v[48:49], v[154:155] op_sel_hi:[1,0]
	v_pk_mul_f32 v[46:47], v[46:47], v[154:155] op_sel_hi:[1,0]
	v_pk_mul_f32 v[44:45], v[44:45], v[154:155] op_sel_hi:[1,0]
	v_pk_mul_f32 v[42:43], v[42:43], v[154:155] op_sel_hi:[1,0]
	v_pk_mul_f32 v[40:41], v[40:41], v[154:155] op_sel_hi:[1,0]
	v_pk_mul_f32 v[38:39], v[38:39], v[154:155] op_sel_hi:[1,0]
	v_pk_mul_f32 v[36:37], v[36:37], v[154:155] op_sel_hi:[1,0]
	v_pk_mul_f32 v[34:35], v[34:35], v[154:155] op_sel_hi:[1,0]
	v_pk_mul_f32 v[32:33], v[32:33], v[154:155] op_sel_hi:[1,0]
	v_pk_mul_f32 v[30:31], v[30:31], v[154:155] op_sel_hi:[1,0]
	v_pk_mul_f32 v[28:29], v[28:29], v[154:155] op_sel_hi:[1,0]
	v_pk_mul_f32 v[26:27], v[26:27], v[154:155] op_sel_hi:[1,0]
	v_pk_mul_f32 v[24:25], v[24:25], v[154:155] op_sel_hi:[1,0]
	v_pk_mul_f32 v[22:23], v[22:23], v[154:155] op_sel_hi:[1,0]
	v_pk_mul_f32 v[20:21], v[20:21], v[154:155] op_sel_hi:[1,0]
	v_pk_mul_f32 v[18:19], v[18:19], v[154:155] op_sel_hi:[1,0]
	v_pk_mul_f32 v[16:17], v[16:17], v[154:155] op_sel_hi:[1,0]
	v_pk_mul_f32 v[14:15], v[14:15], v[154:155] op_sel_hi:[1,0]
	v_pk_mul_f32 v[12:13], v[12:13], v[154:155] op_sel_hi:[1,0]
	v_pk_mul_f32 v[10:11], v[10:11], v[154:155] op_sel_hi:[1,0]
	v_pk_mul_f32 v[8:9], v[8:9], v[154:155] op_sel_hi:[1,0]
	v_pk_mul_f32 v[6:7], v[6:7], v[154:155] op_sel_hi:[1,0]
	v_pk_mul_f32 v[4:5], v[4:5], v[154:155] op_sel_hi:[1,0]
	v_pk_mul_f32 v[2:3], v[2:3], v[154:155] op_sel_hi:[1,0]
	v_pk_mul_f32 v[0:1], v[0:1], v[154:155] op_sel_hi:[1,0]
	v_pk_mul_f32 v[74:75], v[74:75], v[154:155] op_sel_hi:[1,0]
	v_pk_mul_f32 v[72:73], v[72:73], v[154:155] op_sel_hi:[1,0]
	v_pk_mul_f32 v[70:71], v[70:71], v[154:155] op_sel_hi:[1,0]
	v_pk_mul_f32 v[68:69], v[68:69], v[154:155] op_sel_hi:[1,0]
	v_pk_mul_f32 v[66:67], v[66:67], v[154:155] op_sel_hi:[1,0]
	v_pk_mul_f32 v[64:65], v[64:65], v[154:155] op_sel_hi:[1,0]
	v_sub_f32_e32 v109, v109, v155
	v_sub_f32_e32 v108, v108, v155
	v_sub_f32_e32 v107, v107, v155
	v_sub_f32_e32 v106, v106, v155
	v_sub_f32_e32 v105, v105, v155
	v_sub_f32_e32 v104, v104, v155
	v_sub_f32_e32 v103, v103, v155
	v_sub_f32_e32 v102, v102, v155
	v_sub_f32_e32 v101, v101, v155
	v_sub_f32_e32 v100, v100, v155
	v_sub_f32_e32 v99, v99, v155
	v_sub_f32_e32 v98, v98, v155
	v_sub_f32_e32 v97, v97, v155
	v_sub_f32_e32 v96, v96, v155
	v_sub_f32_e32 v95, v95, v155
	v_sub_f32_e32 v94, v94, v155
	v_sub_f32_e32 v93, v93, v155
	v_sub_f32_e32 v92, v92, v155
	v_sub_f32_e32 v91, v91, v155
	v_sub_f32_e32 v90, v90, v155
	v_sub_f32_e32 v89, v89, v155
	v_sub_f32_e32 v88, v88, v155
	v_sub_f32_e32 v87, v87, v155
	v_sub_f32_e32 v86, v86, v155
	v_sub_f32_e32 v85, v85, v155
	v_sub_f32_e32 v84, v84, v155
	v_sub_f32_e32 v83, v83, v155
	v_sub_f32_e32 v82, v82, v155
	v_sub_f32_e32 v81, v81, v155
	v_sub_f32_e32 v80, v80, v155

; #define LAS __attribute__((address_space(3)))
; #define MFMA32(a, b, c) __builtin_amdgcn_mfma_f32_32x32x16_bf16((a), (b), (c), 0, 0, 0)
; __device__ __forceinline__ void at_pv_half(const LAS unsigned char* vp, const bf16x8 (&pf)[4], f32x16 (&O)[4], f32x16& L) {
;     bf16x8 va[8], vb[8];
; #pragma unroll
;     for (int e = 0; e < 2; ++e)
; #pragma unroll
;         for (int ks = 0; ks < 4; ++ks) va[e * 4 + ks] = *(const LAS bf16x8*)(vp + e * 32 * AT_ROWB + 32 * ks);
; #pragma unroll
;     for (int e = 0; e < 2; ++e)
; #pragma unroll
;         for (int ks = 0; ks < 4; ++ks) vb[e * 4 + ks] = *(const LAS bf16x8*)(vp + (2 + e) * 32 * AT_ROWB + 32 * ks);
;     const short one = (short)0x3F80; const bf16x8 ones = {one, one, one, one, one, one, one, one};
;     __builtin_amdgcn_sched_barrier(0);
;     __builtin_amdgcn_s_setprio(1);
; #pragma unroll
;     for (int ks = 0; ks < 4; ++ks) L = MFMA32(ones, pf[ks], L);
;     __builtin_amdgcn_sched_barrier(0);
; #pragma unroll
;     for (int ks = 0; ks < 4; ++ks) { O[0] = MFMA32(va[ks], pf[ks], O[0]); O[1] = MFMA32(va[4 + ks], pf[ks], O[1]); }
; #pragma unroll
;     for (int ks = 0; ks < 4; ++ks) { O[2] = MFMA32(vb[ks], pf[ks], O[2]); O[3] = MFMA32(vb[4 + ks], pf[ks], O[3]); }
;     __builtin_amdgcn_s_setprio(0);
; }
.LBB0_345:
	s_mov_b32 vcc_lo, 0xf0f00f0f
	s_mov_b32 vcc_hi, 0xf0f00f0f
	v_mov_b32_e32 v77, s52
	s_nop 1
	v_cndmask_b32_e32 v76, 0, v77, vcc
	v_mov_b32_e32 v77, v76
	v_mov_b32_e32 v78, v76
	v_mov_b32_e32 v79, v76
	s_lshl_b32 s0, s22, 6
	s_cmp_le_i32 s0, s21
	s_cbranch_scc0 .LBB0_347
	v_add_u32_e32 v166, 0, v228
	v_add_u32_e32 v184, 0xd800, v166
	ds_read_b128 v[96:99], v166 offset:55296
	ds_read_b128 v[100:103], v166 offset:55328
	ds_read_b128 v[104:107], v166 offset:55360
	ds_read_b128 v[108:111], v166 offset:55392
	s_waitcnt vmcnt(0)
	ds_read_b128 v[138:141], v166 offset:59904
	ds_read_b128 v[142:145], v166 offset:59936
	ds_read_b128 v[146:149], v166 offset:59968
	ds_read_b128 v[150:153], v166 offset:60000
	ds_read_b128 v[154:157], v166 offset:64512
	ds_read_b128 v[158:161], v166 offset:64544
	ds_read_b128 v[162:165], v166 offset:64576
	ds_read_b128 v[166:169], v166 offset:64608
	ds_read_b128 v[170:173], v184 offset:13824
	ds_read_b128 v[174:177], v184 offset:13856
	ds_read_b128 v[178:181], v184 offset:13888
	ds_read_b128 v[184:187], v184 offset:13920
	s_setprio 1
	v_mfma_f32_16x16x32_bf16 v[64:67], v[76:79], v[80:83], v[64:67]
	v_mfma_f32_16x16x32_bf16 v[64:67], v[76:79], v[88:91], v[64:67]
	v_mfma_f32_16x16x32_bf16 v[64:67], v[76:79], v[84:87], v[64:67]
	v_mfma_f32_16x16x32_bf16 v[64:67], v[76:79], v[92:95], v[64:67]
	s_waitcnt lgkmcnt(14)
	v_mfma_f32_32x32x16_bf16 v[48:63], v[96:99], v[80:83], v[48:63]
	s_waitcnt lgkmcnt(11)
	v_mfma_f32_32x32x16_bf16 v[32:47], v[138:141], v[80:83], v[32:47]
	s_waitcnt lgkmcnt(7)
	v_mfma_f32_32x32x16_bf16 v[16:31], v[154:157], v[80:83], v[16:31]
	s_waitcnt lgkmcnt(3)
	v_mfma_f32_32x32x16_bf16 v[0:15], v[170:173], v[80:83], v[0:15]
	v_mfma_f32_32x32x16_bf16 v[48:63], v[100:103], v[88:91], v[48:63]
	v_mfma_f32_32x32x16_bf16 v[32:47], v[142:145], v[88:91], v[32:47]
	v_mfma_f32_32x32x16_bf16 v[16:31], v[158:161], v[88:91], v[16:31]
	s_waitcnt lgkmcnt(2)
	v_mfma_f32_32x32x16_bf16 v[0:15], v[174:177], v[88:91], v[0:15]
	v_mfma_f32_32x32x16_bf16 v[48:63], v[104:107], v[84:87], v[48:63]
	v_mfma_f32_32x32x16_bf16 v[32:47], v[146:149], v[84:87], v[32:47]
	v_mfma_f32_32x32x16_bf16 v[16:31], v[162:165], v[84:87], v[16:31]
	s_waitcnt lgkmcnt(1)
	v_mfma_f32_32x32x16_bf16 v[0:15], v[178:181], v[84:87], v[0:15]
	v_mfma_f32_32x32x16_bf16 v[48:63], v[108:111], v[92:95], v[48:63]
	v_mfma_f32_32x32x16_bf16 v[32:47], v[150:153], v[92:95], v[32:47]
	v_mfma_f32_32x32x16_bf16 v[16:31], v[166:169], v[92:95], v[16:31]
	s_waitcnt lgkmcnt(0)
	v_mfma_f32_32x32x16_bf16 v[0:15], v[184:187], v[92:95], v[0:15]
	s_setprio 0

; #define LAS __attribute__((address_space(3)))
; __device__ __forceinline__ float bf2f(bf16_t v) { return __uint_as_float(((unsigned)v) << 16); }
; __device__ __forceinline__ float half_swap_sum(float v) { auto rr = __builtin_amdgcn_permlane32_swap(__float_as_uint(v), __float_as_uint(v), false, false); return __uint_as_float(rr[0]) + __uint_as_float(rr[1]); }
; #define MFMA32(a, b, c) __builtin_amdgcn_mfma_f32_32x32x16_bf16((a), (b), (c), 0, 0, 0)
; __device__ __forceinline__ void at_qk_half(const bool ONLINE, const bool act, const LAS unsigned char* kp, u32x4& pfa, u32x4& pfb, const char* pga, const char* pgb, const bf16x8 (&qf)[4], int q, int q0, int kbase, int hh, float& mrun, f32x16 (&O)[4], f32x16& L, bf16x8 (&pf)[4]) {
;     __builtin_amdgcn_s_setprio(3);
;     bf16x8 kf[8];
; #pragma unroll
;     for (int s = 0; s < 4; ++s) { kf[2 * s] = *(const LAS bf16x8*)(kp + 32 * s); kf[2 * s + 1] = *(const LAS bf16x8*)(kp + 32 * AT_ROWB + 32 * s); }
;     __builtin_amdgcn_sched_barrier(0);
;     pfa = *(const u32x4*)pga; pfb = *(const u32x4*)pgb;
;     __builtin_amdgcn_sched_barrier(0);
;     if (!act) { __builtin_amdgcn_s_setprio(0); return; }
;     f32x16 s0, s1;
; #pragma unroll
;     for (int i = 0; i < 16; ++i) { s0[i] = 0.f; s1[i] = 0.f; }
; #pragma unroll
;     for (int s = 0; s < 4; ++s) { s0 = MFMA32(kf[2 * s], qf[s], s0); s1 = MFMA32(kf[2 * s + 1], qf[s], s1); }
; __device__ __forceinline__ void attn_item(LAS unsigned char* lds, const bf16_t* Q, const bf16_t* Kb, const bf16_t* VT, bf16_t* aout, const float* subg, float lam, float omli, float kbound, int head, int qb) {
;     ...
;     f32x16 O[4];
; #pragma unroll
;     for (int e = 0; e < 4; ++e)
; #pragma unroll
;         for (int i = 0; i < 16; ++i) O[e][i] = 0.f;
;     float qn2 = 0.f;
; #pragma unroll
;     for (int s = 0; s < 4; ++s)
; #pragma unroll
;         for (int e = 0; e < 8; ++e) { const float v = bf2f((bf16_t)qf[s][e]); qn2 += v * v; }
;     const float sbound = __builtin_sqrtf(half_swap_sum(qn2)) * kbound;
;     const bool online = __builtin_amdgcn_ballot_w64(!(sbound <= 100.f)) != 0ull;
;     float mrun = 0.f;
;     f32x16 L;
; #pragma unroll
;     for (int i = 0; i < 16; ++i) L[i] = 0.f;
;     bf16x8 pf[4];
; #pragma unroll
;     for (int i = 0; i < 4; ++i) pf[i] = (bf16x8){0, 0, 0, 0, 0, 0, 0, 0};
.LBB0_348:
	s_and_b64 vcc, exec, s[0:1]
	s_cbranch_vccz .LBB0_364
	s_cmp_lt_i32 s20, 0
	s_cbranch_scc1 .LBB0_362
	s_lshl_b32 s0, s20, 1
	s_and_b32 s0, s0, -4
	s_or_b32 s0, s0, s19
	s_nop 1
	v_mov_b32_e32 v14, v113
	v_mov_b32_e32 v15, v113
	s_add_i32 s0, s0, 2
	v_mov_b32_e32 v0, v113
	v_mov_b32_e32 v1, v113
	v_mov_b32_e32 v2, v113
	v_mov_b32_e32 v3, v113
	v_mov_b32_e32 v4, v113
	v_mov_b32_e32 v5, v113
	v_mov_b32_e32 v6, v113
	v_mov_b32_e32 v7, v113
	v_mov_b32_e32 v8, v113
	v_mov_b32_e32 v9, v113
	v_mov_b32_e32 v10, v113
	v_mov_b32_e32 v11, v113
	v_mov_b32_e32 v12, v113
	v_mov_b32_e32 v13, v113
	v_mov_b64_e32 v[30:31], v[14:15]
	v_mov_b64_e32 v[46:47], v[14:15]
	v_mov_b64_e32 v[62:63], v[14:15]
	v_mov_b64_e32 v[78:79], v[14:15]
	v_lshlrev_b32_e32 v175, 2, v226
	s_max_i32 s19, s0, 1
	s_mov_b32 s38, 0
	v_mov_b32_e32 v174, 0
	s_mov_b32 s20, 63
	v_mov_b32_e32 v92, 0
	v_mov_b32_e32 v93, 0
	v_mov_b32_e32 v94, 0
	v_mov_b32_e32 v95, 0
	v_mov_b32_e32 v84, 0
	v_mov_b32_e32 v85, 0
	v_mov_b32_e32 v86, 0
	v_mov_b32_e32 v87, 0
	v_mov_b32_e32 v88, 0
	v_mov_b32_e32 v89, 0
	v_mov_b32_e32 v90, 0
	v_mov_b32_e32 v91, 0
	v_mov_b32_e32 v80, 0
	v_mov_b32_e32 v81, 0
	v_mov_b32_e32 v82, 0
	v_mov_b32_e32 v83, 0
	v_mov_b64_e32 v[28:29], v[12:13]
	v_mov_b64_e32 v[26:27], v[10:11]
	v_mov_b64_e32 v[24:25], v[8:9]
	v_mov_b64_e32 v[22:23], v[6:7]
	v_mov_b64_e32 v[20:21], v[4:5]
	v_mov_b64_e32 v[18:19], v[2:3]
	v_mov_b64_e32 v[16:17], v[0:1]
	v_mov_b64_e32 v[44:45], v[12:13]
	v_mov_b64_e32 v[42:43], v[10:11]
	v_mov_b64_e32 v[40:41], v[8:9]
	v_mov_b64_e32 v[38:39], v[6:7]
	v_mov_b64_e32 v[36:37], v[4:5]
	v_mov_b64_e32 v[34:35], v[2:3]
	v_mov_b64_e32 v[32:33], v[0:1]
	v_mov_b64_e32 v[60:61], v[12:13]
	v_mov_b64_e32 v[58:59], v[10:11]
	v_mov_b64_e32 v[56:57], v[8:9]
	v_mov_b64_e32 v[54:55], v[6:7]
	v_mov_b64_e32 v[52:53], v[4:5]
	v_mov_b64_e32 v[50:51], v[2:3]
	v_mov_b64_e32 v[48:49], v[0:1]
	v_mov_b64_e32 v[76:77], v[12:13]
	v_mov_b64_e32 v[74:75], v[10:11]
	v_mov_b64_e32 v[72:73], v[8:9]
	v_mov_b64_e32 v[70:71], v[6:7]
	v_mov_b64_e32 v[68:69], v[4:5]
	v_mov_b64_e32 v[66:67], v[2:3]
	v_mov_b64_e32 v[64:65], v[0:1]
	s_mov_b32 vcc_lo, 0xf0f00f0f
	s_mov_b32 vcc_hi, 0xf0f00f0f
	v_mov_b32_e32 v77, s52
	s_nop 1
	v_cndmask_b32_e32 v76, 0, v77, vcc
	v_mov_b32_e32 v77, v76
	v_mov_b32_e32 v78, v76
	v_mov_b32_e32 v79, v76
.LBB0_351:
	s_bitcmp1_b32 s38, 0
	s_cselect_b32 s0, 0x4800, 0
	s_add_i32 s40, s0, 0
	s_sub_i32 s41, s20, 63
	s_cmp_le_i32 s41, s21
	s_cselect_b64 s[0:1], -1, 0
	s_add_i32 s39, s38, 1
	s_min_i32 s58, s39, s22
	s_lshl_b64 s[42:43], s[58:59], 14
	s_cmp_gt_i32 s41, s21
	s_setprio 3
	v_lshl_add_u64 v[100:101], v[208:209], 0, s[42:43]
	v_lshl_add_u64 v[102:103], v[210:211], 0, s[42:43]
	v_add_u32_e32 v104, s40, v229
	s_setprio 3
	ds_read_b128 v[96:99], v104
	ds_read_b128 v[158:161], v104 offset:32
	ds_read_b128 v[154:157], v104 offset:64
	ds_read_b128 v[146:149], v104 offset:96
	ds_read_b128 v[170:173], v104 offset:4608
	ds_read_b128 v[162:165], v104 offset:4640
	ds_read_b128 v[166:169], v104 offset:4672
	ds_read_b128 v[150:153], v104 offset:4704
	global_load_dwordx4 v[138:141], v[100:101], off
	global_load_dwordx4 v[142:145], v[102:103], off
	s_cbranch_scc1 .LBB0_358
	s_cmp_le_i32 s20, s33
	s_cbranch_scc0 .Lmy_slow4
	s_andn2_b64 vcc, exec, s[8:9]
	s_cbranch_vccz .Lmy_slow4
	s_waitcnt lgkmcnt(7)
	v_mfma_f32_32x32x16_bf16 v[96:111], v[96:99], v[126:129], 0
	s_waitcnt lgkmcnt(6)
	v_mfma_f32_32x32x16_bf16 v[96:111], v[158:161], v[122:125], v[96:111]
	s_waitcnt lgkmcnt(5)
	v_mfma_f32_32x32x16_bf16 v[96:111], v[154:157], v[118:121], v[96:111]
	s_waitcnt lgkmcnt(4)
	v_mfma_f32_32x32x16_bf16 v[96:111], v[146:149], v[114:117], v[96:111]
	s_waitcnt lgkmcnt(3)
	v_mfma_f32_32x32x16_bf16 v[80:95], v[170:173], v[126:129], 0
	s_waitcnt lgkmcnt(2)
	v_mfma_f32_32x32x16_bf16 v[80:95], v[162:165], v[122:125], v[80:95]
	s_nop 3
	v_exp_f32_e32 v96, v96
	v_exp_f32_e32 v97, v97
	v_exp_f32_e32 v98, v98
	v_exp_f32_e32 v99, v99
	s_waitcnt lgkmcnt(1)
	v_mfma_f32_32x32x16_bf16 v[80:95], v[166:169], v[118:121], v[80:95]
	v_exp_f32_e32 v100, v100
	v_exp_f32_e32 v101, v101
	v_exp_f32_e32 v102, v102
	v_exp_f32_e32 v103, v103
	s_waitcnt lgkmcnt(0)
	v_mfma_f32_32x32x16_bf16 v[80:95], v[150:153], v[114:117], v[80:95]
	s_setprio 0
	v_exp_f32_e32 v104, v104
	v_exp_f32_e32 v105, v105
	v_exp_f32_e32 v106, v106
	v_exp_f32_e32 v107, v107
	v_exp_f32_e32 v108, v108
	v_exp_f32_e32 v109, v109
	v_exp_f32_e32 v110, v110
	v_exp_f32_e32 v111, v111
	s_nop 3
	v_exp_f32_e32 v146, v80
	v_exp_f32_e32 v147, v81
	v_exp_f32_e32 v148, v82
	v_exp_f32_e32 v149, v83
	v_exp_f32_e32 v150, v84
	v_exp_f32_e32 v151, v85
	v_exp_f32_e32 v152, v86
	v_exp_f32_e32 v153, v87
	v_exp_f32_e32 v154, v88
	v_exp_f32_e32 v155, v89
	v_exp_f32_e32 v156, v90
	v_exp_f32_e32 v157, v91
	v_exp_f32_e32 v158, v92
	v_exp_f32_e32 v159, v93
	v_exp_f32_e32 v160, v94
	v_exp_f32_e32 v161, v95
	v_cvt_pk_bf16_f32 v80, v96, v97
	v_cvt_pk_bf16_f32 v81, v98, v99
	v_cvt_pk_bf16_f32 v82, v100, v101
	v_cvt_pk_bf16_f32 v83, v102, v103
	v_cvt_pk_bf16_f32 v84, v146, v147
	v_cvt_pk_bf16_f32 v85, v148, v149
	v_cvt_pk_bf16_f32 v86, v150, v151
	v_cvt_pk_bf16_f32 v87, v152, v153
	v_cvt_pk_bf16_f32 v88, v104, v105
	v_cvt_pk_bf16_f32 v89, v106, v107
	v_cvt_pk_bf16_f32 v90, v108, v109
	v_cvt_pk_bf16_f32 v91, v110, v111
	v_cvt_pk_bf16_f32 v92, v154, v155
	v_cvt_pk_bf16_f32 v93, v156, v157
	v_cvt_pk_bf16_f32 v94, v158, v159
	v_cvt_pk_bf16_f32 v95, v160, v161
	s_branch .LBB0_358
; #define LAS __attribute__((address_space(3)))
; #define MFMA32(a, b, c) __builtin_amdgcn_mfma_f32_32x32x16_bf16((a), (b), (c), 0, 0, 0)
; __device__ __forceinline__ void at_qk_half(const bool ONLINE, const bool act, const LAS unsigned char* kp, u32x4& pfa, u32x4& pfb, const char* pga, const char* pgb, const bf16x8 (&qf)[4], int q, int q0, int kbase, int hh, float& mrun, f32x16 (&O)[4], f32x16& L, bf16x8 (&pf)[4]) {
;     __builtin_amdgcn_s_setprio(3);
;     bf16x8 kf[8];
; #pragma unroll
;     for (int s = 0; s < 4; ++s) { kf[2 * s] = *(const LAS bf16x8*)(kp + 32 * s); kf[2 * s + 1] = *(const LAS bf16x8*)(kp + 32 * AT_ROWB + 32 * s); }
;     __builtin_amdgcn_sched_barrier(0);
;     pfa = *(const u32x4*)pga; pfb = *(const u32x4*)pgb;
;     __builtin_amdgcn_sched_barrier(0);
;     if (!act) { __builtin_amdgcn_s_setprio(0); return; }
;     f32x16 s0, s1;
; #pragma unroll
;     for (int i = 0; i < 16; ++i) { s0[i] = 0.f; s1[i] = 0.f; }
; #pragma unroll
;     for (int s = 0; s < 4; ++s) { s0 = MFMA32(kf[2 * s], qf[s], s0); s1 = MFMA32(kf[2 * s + 1], qf[s], s1); }
;     __builtin_amdgcn_s_setprio(0);
;     if (kbase + 63 > q0) {
;         const int kb = kbase + 4 * hh;
; #pragma unroll
;         for (int i = 0; i < 16; ++i) { const int kv = kb + (i & 3) + 8 * (i >> 2); if (kv > q) s0[i] = -INFINITY; if (kv + 32 > q) s1[i] = -INFINITY; }
;     }
.Lmy_slow4:
	s_waitcnt lgkmcnt(7)
	v_mfma_f32_32x32x16_bf16 v[96:111], v[96:99], v[126:129], 0
	s_waitcnt lgkmcnt(3)
	v_mfma_f32_32x32x16_bf16 v[80:95], v[170:173], v[126:129], 0
	v_mfma_f32_32x32x16_bf16 v[96:111], v[158:161], v[122:125], v[96:111]
	s_waitcnt lgkmcnt(2)
	v_mfma_f32_32x32x16_bf16 v[80:95], v[162:165], v[122:125], v[80:95]
	v_mfma_f32_32x32x16_bf16 v[96:111], v[154:157], v[118:121], v[96:111]
	s_waitcnt lgkmcnt(1)
	v_mfma_f32_32x32x16_bf16 v[80:95], v[166:169], v[118:121], v[80:95]
	v_mfma_f32_32x32x16_bf16 v[96:111], v[146:149], v[114:117], v[96:111]
	s_waitcnt lgkmcnt(0)
	v_mfma_f32_32x32x16_bf16 v[80:95], v[150:153], v[114:117], v[80:95]
	s_setprio 0
	s_cmp_le_i32 s20, s33
	s_cbranch_scc1 .LBB0_354
	v_add_u32_e32 v146, s20, v175
	v_subrev_u32_e32 v148, 31, v146
	v_subrev_u32_e32 v147, 63, v146
	v_cmp_le_i32_e32 vcc, v148, v202
	s_nop 4
	v_cndmask_b32_e32 v80, v221, v80, vcc
	v_cmp_lt_i32_e32 vcc, v147, v202
	s_nop 1
	v_cndmask_b32_e32 v97, v221, v97, vcc
	v_cmp_le_i32_e32 vcc, v147, v202
	v_subrev_u32_e32 v147, 30, v146
	s_nop 0
	v_cndmask_b32_e32 v96, v221, v96, vcc
	v_cmp_le_i32_e32 vcc, v147, v202
	v_subrev_u32_e32 v147, 61, v146
	s_nop 0
	v_cndmask_b32_e32 v81, v221, v81, vcc
	v_cmp_le_i32_e32 vcc, v147, v202
	v_subrev_u32_e32 v147, 29, v146
	s_nop 0
	v_cndmask_b32_e32 v98, v221, v98, vcc
	v_cmp_le_i32_e32 vcc, v147, v202
	v_subrev_u32_e32 v147, 60, v146
	s_nop 0
	v_cndmask_b32_e32 v82, v221, v82, vcc
	v_cmp_le_i32_e32 vcc, v147, v202
	v_subrev_u32_e32 v147, 28, v146
	s_nop 0
	v_cndmask_b32_e32 v99, v221, v99, vcc
	v_cmp_le_i32_e32 vcc, v147, v202
	v_subrev_u32_e32 v147, 55, v146
	s_nop 0
	v_cndmask_b32_e32 v83, v221, v83, vcc
	v_cmp_le_i32_e32 vcc, v147, v202
	v_subrev_u32_e32 v147, 23, v146
	s_nop 0
	v_cndmask_b32_e32 v100, v221, v100, vcc
	v_cmp_le_i32_e32 vcc, v147, v202
	v_subrev_u32_e32 v147, 54, v146
	s_nop 0
	v_cndmask_b32_e32 v84, v221, v84, vcc
	v_cmp_le_i32_e32 vcc, v147, v202
	v_subrev_u32_e32 v147, 22, v146
	s_nop 0
	v_cndmask_b32_e32 v101, v221, v101, vcc
	v_cmp_le_i32_e32 vcc, v147, v202
	v_subrev_u32_e32 v147, 53, v146
	s_nop 0
	v_cndmask_b32_e32 v85, v221, v85, vcc
	v_cmp_le_i32_e32 vcc, v147, v202
	v_subrev_u32_e32 v147, 21, v146
	s_nop 0
	v_cndmask_b32_e32 v102, v221, v102, vcc
	v_cmp_le_i32_e32 vcc, v147, v202
	v_subrev_u32_e32 v147, 52, v146
	s_nop 0
	v_cndmask_b32_e32 v86, v221, v86, vcc
	v_cmp_le_i32_e32 vcc, v147, v202
	v_subrev_u32_e32 v147, 20, v146
	s_nop 0
	v_cndmask_b32_e32 v103, v221, v103, vcc
	v_cmp_le_i32_e32 vcc, v147, v202
	v_subrev_u32_e32 v147, 47, v146
	s_nop 0
	v_cndmask_b32_e32 v87, v221, v87, vcc
	v_cmp_le_i32_e32 vcc, v147, v202
	v_add_u32_e32 v147, -15, v146
	s_nop 0
	v_cndmask_b32_e32 v104, v221, v104, vcc
	v_cmp_le_i32_e32 vcc, v147, v202
	v_subrev_u32_e32 v147, 46, v146
	s_nop 0
	v_cndmask_b32_e32 v88, v221, v88, vcc
	v_cmp_le_i32_e32 vcc, v147, v202
	v_add_u32_e32 v147, -14, v146
	s_nop 0
	v_cndmask_b32_e32 v105, v221, v105, vcc
	v_cmp_le_i32_e32 vcc, v147, v202
	v_subrev_u32_e32 v147, 45, v146
	s_nop 0
	v_cndmask_b32_e32 v89, v221, v89, vcc
	v_cmp_le_i32_e32 vcc, v147, v202
	v_add_u32_e32 v147, -13, v146
	s_nop 0
	v_cndmask_b32_e32 v106, v221, v106, vcc
	v_cmp_le_i32_e32 vcc, v147, v202
	v_subrev_u32_e32 v147, 44, v146
	s_nop 0
	v_cndmask_b32_e32 v90, v221, v90, vcc
	v_cmp_le_i32_e32 vcc, v147, v202
	v_add_u32_e32 v147, -12, v146
	s_nop 0
	v_cndmask_b32_e32 v107, v221, v107, vcc
	v_cmp_le_i32_e32 vcc, v147, v202
	v_subrev_u32_e32 v147, 39, v146
	s_nop 0
	v_cndmask_b32_e32 v91, v221, v91, vcc
	v_cmp_le_i32_e32 vcc, v147, v202
	v_add_u32_e32 v147, -7, v146
	s_nop 0
	v_cndmask_b32_e32 v108, v221, v108, vcc
	v_cmp_le_i32_e32 vcc, v147, v202
	v_subrev_u32_e32 v147, 38, v146
	s_nop 0
	v_cndmask_b32_e32 v92, v221, v92, vcc
	v_cmp_le_i32_e32 vcc, v147, v202
	v_add_u32_e32 v147, -6, v146
	s_nop 0
	v_cndmask_b32_e32 v109, v221, v109, vcc
	v_cmp_le_i32_e32 vcc, v147, v202
	v_subrev_u32_e32 v147, 37, v146
	s_nop 0
	v_cndmask_b32_e32 v93, v221, v93, vcc
	v_cmp_le_i32_e32 vcc, v147, v202
	v_add_u32_e32 v147, -5, v146
	s_nop 0
	v_cndmask_b32_e32 v110, v221, v110, vcc
	v_cmp_le_i32_e32 vcc, v147, v202
	v_subrev_u32_e32 v147, 36, v146
	v_add_u32_e32 v146, -4, v146
	v_cndmask_b32_e32 v94, v221, v94, vcc
	v_cmp_le_i32_e32 vcc, v147, v202
	s_nop 1
	v_cndmask_b32_e32 v111, v221, v111, vcc
	v_cmp_le_i32_e32 vcc, v146, v202
	s_nop 1
	v_cndmask_b32_e32 v95, v221, v95, vcc
; __device__ __forceinline__ float half_swap_max(float v) { auto rr = __builtin_amdgcn_permlane32_swap(__float_as_uint(v), __float_as_uint(v), false, false); return fmaxf(__uint_as_float(rr[0]), __uint_as_float(rr[1])); }
; __device__ __forceinline__ float at_max3(float a, float b, float c) { float r; asm("v_max3_f32 %0, %1, %2, %3" : "=v"(r) : "v"(a), "v"(b), "v"(c)); return r; }
; __device__ __forceinline__ void at_qk_half(const bool ONLINE, const bool act, const LAS unsigned char* kp, u32x4& pfa, u32x4& pfb, const char* pga, const char* pgb, const bf16x8 (&qf)[4], int q, int q0, int kbase, int hh, float& mrun, f32x16 (&O)[4], f32x16& L, bf16x8 (&pf)[4]) {
;     ...
;     if (ONLINE) {
; #pragma unroll
;         for (int i = 0; i < 16; ++i) { s0[i] -= mrun; s1[i] -= mrun; }
;         float mx = fmaxf(s0[0], s1[0]);
; #pragma unroll
;         for (int i = 1; i < 16; ++i) mx = at_max3(mx, s0[i], s1[i]);
;         mx = half_swap_max(mx);
;         if (__builtin_amdgcn_ballot_w64(mx > 8.f) != 0ull) {
;             const float d = fmaxf(mx, 0.f); const float alpha = __builtin_amdgcn_exp2f(-d); mrun += d;
; #pragma unroll
;             for (int e = 0; e < 4; ++e)
; #pragma unroll
;                 for (int i = 0; i < 16; ++i) O[e][i] *= alpha;
; #pragma unroll
;             for (int i = 0; i < 16; ++i) { L[i] *= alpha; s0[i] -= d; s1[i] -= d; }
;         }
;     }
.LBB0_354:
	s_andn2_b64 vcc, exec, s[8:9]
	s_cbranch_vccnz .LBB0_357
	s_nop 4
	v_pk_add_f32 v[96:97], v[96:97], v[174:175] op_sel_hi:[1,0] neg_lo:[0,1] neg_hi:[0,1]
	s_nop 0
	v_pk_add_f32 v[80:81], v[80:81], v[174:175] op_sel_hi:[1,0] neg_lo:[0,1] neg_hi:[0,1]
	v_pk_add_f32 v[98:99], v[98:99], v[174:175] op_sel_hi:[1,0] neg_lo:[0,1] neg_hi:[0,1]
	v_max_f32_e32 v146, v96, v80
	v_max3_f32 v146, v146, v97, v81
	v_pk_add_f32 v[82:83], v[82:83], v[174:175] op_sel_hi:[1,0] neg_lo:[0,1] neg_hi:[0,1]
	v_pk_add_f32 v[100:101], v[100:101], v[174:175] op_sel_hi:[1,0] neg_lo:[0,1] neg_hi:[0,1]
	v_max3_f32 v146, v146, v98, v82
	v_pk_add_f32 v[84:85], v[84:85], v[174:175] op_sel_hi:[1,0] neg_lo:[0,1] neg_hi:[0,1]
	v_max3_f32 v146, v146, v99, v83
	v_pk_add_f32 v[102:103], v[102:103], v[174:175] op_sel_hi:[1,0] neg_lo:[0,1] neg_hi:[0,1]
	v_max3_f32 v146, v146, v100, v84
	v_pk_add_f32 v[86:87], v[86:87], v[174:175] op_sel_hi:[1,0] neg_lo:[0,1] neg_hi:[0,1]
	v_max3_f32 v146, v146, v101, v85
	v_pk_add_f32 v[104:105], v[104:105], v[174:175] op_sel_hi:[1,0] neg_lo:[0,1] neg_hi:[0,1]
	v_max3_f32 v146, v146, v102, v86
	v_pk_add_f32 v[88:89], v[88:89], v[174:175] op_sel_hi:[1,0] neg_lo:[0,1] neg_hi:[0,1]
	v_max3_f32 v146, v146, v103, v87
	v_pk_add_f32 v[106:107], v[106:107], v[174:175] op_sel_hi:[1,0] neg_lo:[0,1] neg_hi:[0,1]
	v_max3_f32 v146, v146, v104, v88
	v_pk_add_f32 v[90:91], v[90:91], v[174:175] op_sel_hi:[1,0] neg_lo:[0,1] neg_hi:[0,1]
	v_max3_f32 v146, v146, v105, v89
	v_pk_add_f32 v[108:109], v[108:109], v[174:175] op_sel_hi:[1,0] neg_lo:[0,1] neg_hi:[0,1]
	v_max3_f32 v146, v146, v106, v90
	v_pk_add_f32 v[92:93], v[92:93], v[174:175] op_sel_hi:[1,0] neg_lo:[0,1] neg_hi:[0,1]
	v_max3_f32 v146, v146, v107, v91
	v_pk_add_f32 v[110:111], v[110:111], v[174:175] op_sel_hi:[1,0] neg_lo:[0,1] neg_hi:[0,1]
	v_max3_f32 v146, v146, v108, v92
	v_pk_add_f32 v[94:95], v[94:95], v[174:175] op_sel_hi:[1,0] neg_lo:[0,1] neg_hi:[0,1]
	v_max3_f32 v146, v146, v109, v93
	s_nop 0
	v_max3_f32 v146, v146, v110, v94
	s_nop 0
	v_max3_f32 v146, v146, v111, v95
	s_nop 0
	v_mov_b32_e32 v147, v146
	s_nop 1
	v_permlane32_swap_b32_e32 v146, v147
	v_max_f32_e32 v147, v147, v147
	v_max_f32_e32 v146, v146, v146
	v_max_f32_e32 v146, v146, v147
	v_cmp_lt_f32_e32 vcc, s25, v146
	s_cbranch_vccz .LBB0_357
	v_max_f32_e32 v146, v146, v146
	v_max_f32_e32 v147, 0, v146
	v_exp_f32_e64 v146, -v147
	v_add_f32_e32 v174, v174, v147
	v_sub_f32_e32 v111, v111, v147
	v_sub_f32_e32 v110, v110, v147
	v_pk_mul_f32 v[62:63], v[62:63], v[146:147] op_sel_hi:[1,0]
	v_pk_mul_f32 v[60:61], v[60:61], v[146:147] op_sel_hi:[1,0]
	v_pk_mul_f32 v[58:59], v[58:59], v[146:147] op_sel_hi:[1,0]
	v_pk_mul_f32 v[56:57], v[56:57], v[146:147] op_sel_hi:[1,0]
	v_pk_mul_f32 v[54:55], v[54:55], v[146:147] op_sel_hi:[1,0]
	v_pk_mul_f32 v[52:53], v[52:53], v[146:147] op_sel_hi:[1,0]
	v_pk_mul_f32 v[50:51], v[50:51], v[146:147] op_sel_hi:[1,0]
	v_pk_mul_f32 v[48:49], v[48:49], v[146:147] op_sel_hi:[1,0]
	v_pk_mul_f32 v[46:47], v[46:47], v[146:147] op_sel_hi:[1,0]
	v_pk_mul_f32 v[44:45], v[44:45], v[146:147] op_sel_hi:[1,0]
	v_pk_mul_f32 v[42:43], v[42:43], v[146:147] op_sel_hi:[1,0]
	v_pk_mul_f32 v[40:41], v[40:41], v[146:147] op_sel_hi:[1,0]
	v_pk_mul_f32 v[38:39], v[38:39], v[146:147] op_sel_hi:[1,0]
	v_pk_mul_f32 v[36:37], v[36:37], v[146:147] op_sel_hi:[1,0]
	v_pk_mul_f32 v[34:35], v[34:35], v[146:147] op_sel_hi:[1,0]
	v_pk_mul_f32 v[32:33], v[32:33], v[146:147] op_sel_hi:[1,0]
	v_pk_mul_f32 v[30:31], v[30:31], v[146:147] op_sel_hi:[1,0]
	v_pk_mul_f32 v[28:29], v[28:29], v[146:147] op_sel_hi:[1,0]
	v_pk_mul_f32 v[26:27], v[26:27], v[146:147] op_sel_hi:[1,0]
	v_pk_mul_f32 v[24:25], v[24:25], v[146:147] op_sel_hi:[1,0]
	v_pk_mul_f32 v[22:23], v[22:23], v[146:147] op_sel_hi:[1,0]
	v_pk_mul_f32 v[20:21], v[20:21], v[146:147] op_sel_hi:[1,0]
	v_pk_mul_f32 v[18:19], v[18:19], v[146:147] op_sel_hi:[1,0]
	v_pk_mul_f32 v[16:17], v[16:17], v[146:147] op_sel_hi:[1,0]
	v_pk_mul_f32 v[14:15], v[14:15], v[146:147] op_sel_hi:[1,0]
	v_pk_mul_f32 v[12:13], v[12:13], v[146:147] op_sel_hi:[1,0]
	v_pk_mul_f32 v[10:11], v[10:11], v[146:147] op_sel_hi:[1,0]
	v_pk_mul_f32 v[8:9], v[8:9], v[146:147] op_sel_hi:[1,0]
	v_pk_mul_f32 v[6:7], v[6:7], v[146:147] op_sel_hi:[1,0]
	v_pk_mul_f32 v[4:5], v[4:5], v[146:147] op_sel_hi:[1,0]
	v_pk_mul_f32 v[2:3], v[2:3], v[146:147] op_sel_hi:[1,0]
	v_pk_mul_f32 v[0:1], v[0:1], v[146:147] op_sel_hi:[1,0]
	v_pk_mul_f32 v[74:75], v[74:75], v[146:147] op_sel_hi:[1,0]
	v_pk_mul_f32 v[72:73], v[72:73], v[146:147] op_sel_hi:[1,0]
	v_pk_mul_f32 v[70:71], v[70:71], v[146:147] op_sel_hi:[1,0]
	v_pk_mul_f32 v[68:69], v[68:69], v[146:147] op_sel_hi:[1,0]
	v_pk_mul_f32 v[66:67], v[66:67], v[146:147] op_sel_hi:[1,0]
	v_pk_mul_f32 v[64:65], v[64:65], v[146:147] op_sel_hi:[1,0]
	v_sub_f32_e32 v109, v109, v147
	v_sub_f32_e32 v108, v108, v147
	v_sub_f32_e32 v107, v107, v147
	v_sub_f32_e32 v106, v106, v147
	v_sub_f32_e32 v105, v105, v147
	v_sub_f32_e32 v104, v104, v147
	v_sub_f32_e32 v103, v103, v147
	v_sub_f32_e32 v102, v102, v147
	v_sub_f32_e32 v101, v101, v147
	v_sub_f32_e32 v100, v100, v147
	v_sub_f32_e32 v99, v99, v147
	v_sub_f32_e32 v98, v98, v147
	v_sub_f32_e32 v97, v97, v147
	v_sub_f32_e32 v96, v96, v147
	v_sub_f32_e32 v95, v95, v147
	v_sub_f32_e32 v94, v94, v147
	v_sub_f32_e32 v93, v93, v147
	v_sub_f32_e32 v92, v92, v147
	v_sub_f32_e32 v91, v91, v147
	v_sub_f32_e32 v90, v90, v147
	v_sub_f32_e32 v89, v89, v147
	v_sub_f32_e32 v88, v88, v147
	v_sub_f32_e32 v87, v87, v147
	v_sub_f32_e32 v86, v86, v147
	v_sub_f32_e32 v85, v85, v147
	v_sub_f32_e32 v84, v84, v147
	v_sub_f32_e32 v83, v83, v147
	v_sub_f32_e32 v82, v82, v147
	v_sub_f32_e32 v81, v81, v147
	v_sub_f32_e32 v80, v80, v147

; #define LAS __attribute__((address_space(3)))
; #define MFMA32(a, b, c) __builtin_amdgcn_mfma_f32_32x32x16_bf16((a), (b), (c), 0, 0, 0)
; #define AT_ISSUE_K(jn) do { const int jc_ = (jn) < ntm1 ? (jn) : ntm1; const size_t ko_ = (size_t)jc_ * 8192; ks0 = *(const u32x4*)(bK1 + ko_ + koff); ks1 = *(const u32x4*)(bK2 + ko_ + koff); } while (0)
; __device__ __forceinline__ void at_pv_half(const LAS unsigned char* vp, const bf16x8 (&pf)[4], f32x16 (&O)[4], f32x16& L) {
;     bf16x8 va[8], vb[8];
; #pragma unroll
;     for (int e = 0; e < 2; ++e)
; #pragma unroll
;         for (int ks = 0; ks < 4; ++ks) va[e * 4 + ks] = *(const LAS bf16x8*)(vp + e * 32 * AT_ROWB + 32 * ks);
; #pragma unroll
;     for (int e = 0; e < 2; ++e)
; #pragma unroll
;         for (int ks = 0; ks < 4; ++ks) vb[e * 4 + ks] = *(const LAS bf16x8*)(vp + (2 + e) * 32 * AT_ROWB + 32 * ks);
;     const short one = (short)0x3F80; const bf16x8 ones = {one, one, one, one, one, one, one, one};
;     __builtin_amdgcn_sched_barrier(0);
;     __builtin_amdgcn_s_setprio(1);
; #pragma unroll
;     for (int ks = 0; ks < 4; ++ks) L = MFMA32(ones, pf[ks], L);
;     __builtin_amdgcn_sched_barrier(0);
; #pragma unroll
;     for (int ks = 0; ks < 4; ++ks) { O[0] = MFMA32(va[ks], pf[ks], O[0]); O[1] = MFMA32(va[4 + ks], pf[ks], O[1]); }
; #pragma unroll
;     for (int ks = 0; ks < 4; ++ks) { O[2] = MFMA32(vb[ks], pf[ks], O[2]); O[3] = MFMA32(vb[4 + ks], pf[ks], O[3]); }
;     __builtin_amdgcn_s_setprio(0);
; }
; __device__ __forceinline__ void attn_item(LAS unsigned char* lds, const bf16_t* Q, const bf16_t* Kb, const bf16_t* VT, bf16_t* aout, const float* subg, float lam, float omli, float kbound, int head, int qb) {
;     ...
;             __builtin_amdgcn_s_setprio(3);
;             { const int jc_ = (j + 1) < ntm1 ? (j + 1) : ntm1; const size_t vo_ = (size_t)jc_ * 16384; const char* pga = bV0 + vo_ + voff; const char* pgb = bV1 + vo_ + voff;
;               at_qk_half(online, act, stg + kfo, vs0, vs1, pga, pgb, qf, q, q0, kbase, hh, mrun, O, L, pf); }
;             __builtin_amdgcn_s_setprio(3);
;             AT_WRITE_K(j + 1);
;             __syncthreads();
;             __builtin_amdgcn_s_setprio(0);
;             AT_ISSUE_K(j + 2);
;             if (act) at_pv_half(stg + vfo, pf, O, L);
.LBB0_358:
	s_setprio 0
	s_setprio 3
	s_bitcmp1_b32 s39, 0
	s_cselect_b32 s41, 0x4800, 0
	s_waitcnt lgkmcnt(7)
	v_add_u32_e32 v96, s41, v213
	s_waitcnt vmcnt(3)
	ds_write_b128 v96, v[130:133]
	s_waitcnt vmcnt(2)
	ds_write_b128 v96, v[134:137] offset:9216
	s_waitcnt lgkmcnt(0)
	s_barrier
	s_setprio 0
	s_add_i32 s38, s38, 2
	s_min_i32 s58, s38, s22
	s_lshl_b64 s[42:43], s[58:59], 13
	v_lshl_add_u64 v[98:99], v[204:205], 0, s[42:43]
	v_lshl_add_u64 v[100:101], v[206:207], 0, s[42:43]
	global_load_dwordx4 v[130:133], v[98:99], off
	global_load_dwordx4 v[134:137], v[100:101], off
	s_andn2_b64 vcc, exec, s[0:1]
	s_cbranch_vccnz .LBB0_360
	v_add_u32_e32 v97, s40, v228
	ds_read_b128 v[98:101], v97 offset:36864
	ds_read_b128 v[150:153], v97 offset:41472
	ds_read_b128 v[166:169], v97 offset:46080
	ds_read_b128 v[230:233], v97 offset:50688
	ds_read_b128 v[102:105], v97 offset:36896
	ds_read_b128 v[154:157], v97 offset:41504
	ds_read_b128 v[170:173], v97 offset:46112
	ds_read_b128 v[234:237], v97 offset:50720
	ds_read_b128 v[106:109], v97 offset:36928
	ds_read_b128 v[158:161], v97 offset:41536
	ds_read_b128 v[176:179], v97 offset:46144
	ds_read_b128 v[238:241], v97 offset:50752
	ds_read_b128 v[146:149], v97 offset:36960
	ds_read_b128 v[162:165], v97 offset:41568
	ds_read_b128 v[184:187], v97 offset:46176
	ds_read_b128 v[242:245], v97 offset:50784
	s_setprio 1
	v_mfma_f32_16x16x32_bf16 v[64:67], v[76:79], v[80:83], v[64:67]
	v_mfma_f32_16x16x32_bf16 v[64:67], v[76:79], v[88:91], v[64:67]
	v_mfma_f32_16x16x32_bf16 v[64:67], v[76:79], v[84:87], v[64:67]
	v_mfma_f32_16x16x32_bf16 v[64:67], v[76:79], v[92:95], v[64:67]
	s_waitcnt lgkmcnt(15)
	v_mfma_f32_32x32x16_bf16 v[48:63], v[98:101], v[80:83], v[48:63]
	s_waitcnt lgkmcnt(14)
	v_mfma_f32_32x32x16_bf16 v[32:47], v[150:153], v[80:83], v[32:47]
	s_waitcnt lgkmcnt(13)
	v_mfma_f32_32x32x16_bf16 v[16:31], v[166:169], v[80:83], v[16:31]
	s_waitcnt lgkmcnt(12)
	v_mfma_f32_32x32x16_bf16 v[0:15], v[230:233], v[80:83], v[0:15]
	s_waitcnt lgkmcnt(11)
	v_mfma_f32_32x32x16_bf16 v[48:63], v[102:105], v[88:91], v[48:63]
	s_waitcnt lgkmcnt(10)
	v_mfma_f32_32x32x16_bf16 v[32:47], v[154:157], v[88:91], v[32:47]
	s_waitcnt lgkmcnt(9)
	v_mfma_f32_32x32x16_bf16 v[16:31], v[170:173], v[88:91], v[16:31]
	s_waitcnt lgkmcnt(8)
	v_mfma_f32_32x32x16_bf16 v[0:15], v[234:237], v[88:91], v[0:15]
	s_waitcnt lgkmcnt(7)
	v_mfma_f32_32x32x16_bf16 v[48:63], v[106:109], v[84:87], v[48:63]
	s_waitcnt lgkmcnt(6)
	v_mfma_f32_32x32x16_bf16 v[32:47], v[158:161], v[84:87], v[32:47]
	s_waitcnt lgkmcnt(5)
	v_mfma_f32_32x32x16_bf16 v[16:31], v[176:179], v[84:87], v[16:31]
	s_waitcnt lgkmcnt(4)
	v_mfma_f32_32x32x16_bf16 v[0:15], v[238:241], v[84:87], v[0:15]
	s_waitcnt lgkmcnt(3)
	v_mfma_f32_32x32x16_bf16 v[48:63], v[146:149], v[92:95], v[48:63]
	s_waitcnt lgkmcnt(2)
	v_mfma_f32_32x32x16_bf16 v[32:47], v[162:165], v[92:95], v[32:47]
	s_waitcnt lgkmcnt(1)
	v_mfma_f32_32x32x16_bf16 v[16:31], v[184:187], v[92:95], v[16:31]
	s_waitcnt lgkmcnt(0)
	v_mfma_f32_32x32x16_bf16 v[0:15], v[242:245], v[92:95], v[0:15]
	s_setprio 0
